# v16 + C=0 first-iteration peel: the 128 accumulator-zeroing v_movs before each of 7 GEMM K-loops are removed; a peeled copy of the first K-iteration gives each accumulator's first MFMA the inline cons
# speedup vs baseline: 1.0036x; 1.0036x over previous
.LBB0_108:
	s_ashr_i32 s15, s14, 31
	s_lshl_b64 s[16:17], s[14:15], 21
	v_readlane_b32 s18, v251, 17
	v_readlane_b32 s19, v251, 18
	s_add_u32 s16, s18, s16
	s_addc_u32 s17, s19, s17
	s_and_b64 s[18:19], s[2:3], exec
	s_cselect_b32 s15, s17, s21
	s_cselect_b32 s42, s16, s20
	s_ashr_i32 s13, s12, 31
	s_lshl_b64 s[18:19], s[12:13], 21
	s_add_u32 s18, s76, s18
	s_addc_u32 s19, s77, s19
	s_and_b64 s[24:25], s[2:3], exec
	s_cselect_b32 s13, s19, s23
	s_cselect_b32 s43, s18, s22
	s_add_u32 s20, s20, 0x104000
	s_addc_u32 s21, s21, 0
	s_add_u32 s44, s22, 0x8000
	s_addc_u32 s45, s23, 0
	s_mov_b32 s46, -2
	ds_read_b128 v[130:133], v158
	ds_read_b128 v[162:165], v158 offset:1024
	ds_read_b128 v[166:169], v158 offset:2048
	ds_read_b128 v[170:173], v158 offset:3072
	ds_read_b128 v[174:177], v159
	ds_read_b128 v[178:181], v159 offset:1024
	ds_read_b128 v[182:185], v159 offset:2048
	ds_read_b128 v[186:189], v159 offset:3072
	s_add_u32 s22, s20, 0xfff04000
	s_addc_u32 s23, s21, -1
	s_cmp_eq_u32 s46, 60
	s_cselect_b32 s26, s42, s22
	s_cselect_b32 s27, s15, s23
	s_cselect_b32 s24, s43, s44
	s_cselect_b32 s25, s13, s45
	s_add_u32 s22, s26, 0x4000
	s_addc_u32 s23, s27, 0
	s_add_i32 m0, s29, 0xc000
	ds_read_b128 v[190:193], v160
	ds_read_b128 v[194:197], v160 offset:1024
	ds_read_b128 v[198:201], v160 offset:2048
	ds_read_b128 v[202:205], v160 offset:3072
	ds_read_b128 v[206:209], v160 offset:4096
	ds_read_b128 v[210:213], v160 offset:5120
	ds_read_b128 v[214:217], v160 offset:6144
	ds_read_b128 v[218:221], v160 offset:7168
	global_load_lds_dwordx4 v146, s[20:21]
	s_add_i32 m0, s29, 0xe000
	s_nop 0
	global_load_lds_dwordx4 v148, s[20:21]
	s_waitcnt vmcnt(8)
	s_waitcnt lgkmcnt(0)
	s_barrier
	s_waitcnt lgkmcnt(0)
	v_mfma_f32_16x16x32_bf16 v[62:65], v[130:133], v[190:193], 0
	v_mfma_f32_16x16x32_bf16 v[62:65], v[162:165], v[194:197], v[62:65]
	v_mfma_f32_16x16x32_bf16 v[58:61], v[166:169], v[190:193], 0
	v_mfma_f32_16x16x32_bf16 v[58:61], v[170:173], v[194:197], v[58:61]
	v_mfma_f32_16x16x32_bf16 v[54:57], v[130:133], v[198:201], 0
	v_mfma_f32_16x16x32_bf16 v[54:57], v[162:165], v[202:205], v[54:57]
	v_mfma_f32_16x16x32_bf16 v[50:53], v[166:169], v[198:201], 0
	v_mfma_f32_16x16x32_bf16 v[50:53], v[170:173], v[202:205], v[50:53]
	v_mfma_f32_16x16x32_bf16 v[46:49], v[130:133], v[206:209], 0
	v_mfma_f32_16x16x32_bf16 v[46:49], v[162:165], v[210:213], v[46:49]
	v_mfma_f32_16x16x32_bf16 v[42:45], v[166:169], v[206:209], 0
	v_mfma_f32_16x16x32_bf16 v[42:45], v[170:173], v[210:213], v[42:45]
	v_mfma_f32_16x16x32_bf16 v[38:41], v[130:133], v[214:217], 0
	v_mfma_f32_16x16x32_bf16 v[38:41], v[162:165], v[218:221], v[38:41]
	v_mfma_f32_16x16x32_bf16 v[34:37], v[166:169], v[214:217], 0
	v_mfma_f32_16x16x32_bf16 v[34:37], v[170:173], v[218:221], v[34:37]
	v_mfma_f32_16x16x32_bf16 v[126:129], v[174:177], v[190:193], 0
	v_mfma_f32_16x16x32_bf16 v[126:129], v[178:181], v[194:197], v[126:129]
	v_mfma_f32_16x16x32_bf16 v[122:125], v[182:185], v[190:193], 0
	v_mfma_f32_16x16x32_bf16 v[122:125], v[186:189], v[194:197], v[122:125]
	v_mfma_f32_16x16x32_bf16 v[118:121], v[174:177], v[198:201], 0
	v_mfma_f32_16x16x32_bf16 v[118:121], v[178:181], v[202:205], v[118:121]
	v_mfma_f32_16x16x32_bf16 v[114:117], v[182:185], v[198:201], 0
	v_mfma_f32_16x16x32_bf16 v[114:117], v[186:189], v[202:205], v[114:117]
	v_mfma_f32_16x16x32_bf16 v[110:113], v[174:177], v[206:209], 0
	v_mfma_f32_16x16x32_bf16 v[110:113], v[178:181], v[210:213], v[110:113]
	v_mfma_f32_16x16x32_bf16 v[106:109], v[182:185], v[206:209], 0
	v_mfma_f32_16x16x32_bf16 v[106:109], v[186:189], v[210:213], v[106:109]
	v_mfma_f32_16x16x32_bf16 v[102:105], v[174:177], v[214:217], 0
	v_mfma_f32_16x16x32_bf16 v[102:105], v[178:181], v[218:221], v[102:105]
	v_mfma_f32_16x16x32_bf16 v[98:101], v[182:185], v[214:217], 0
	v_mfma_f32_16x16x32_bf16 v[98:101], v[186:189], v[218:221], v[98:101]
	s_barrier
	s_add_i32 s47, s36, s28
	s_mov_b32 m0, s47
	ds_read_b128 v[190:193], v160 offset:16384
	ds_read_b128 v[194:197], v160 offset:17408
	ds_read_b128 v[198:201], v160 offset:18432
	ds_read_b128 v[202:205], v160 offset:19456
	ds_read_b128 v[206:209], v160 offset:20480
	ds_read_b128 v[210:213], v160 offset:21504
	ds_read_b128 v[214:217], v160 offset:22528
	ds_read_b128 v[218:221], v160 offset:23552
	global_load_lds_dwordx4 v138, s[24:25]
	s_add_i32 m0, s47, 0x2000
	s_add_u32 s48, s24, 0x100000
	s_addc_u32 s49, s25, 0
	s_add_i32 s47, s37, s28
	global_load_lds_dwordx4 v134, s[24:25]
	s_mov_b32 m0, s47
	s_nop 0
	global_load_lds_dwordx4 v138, s[48:49]
	s_add_i32 m0, s47, 0x2000
	s_nop 0
	global_load_lds_dwordx4 v134, s[48:49]
	s_mov_b32 m0, s29
	s_nop 0
	global_load_lds_dwordx4 v140, s[26:27]
	s_mov_b32 m0, s30
	s_nop 0
	global_load_lds_dwordx4 v136, s[26:27]
	s_waitcnt vmcnt(8)
	s_waitcnt lgkmcnt(0)
	s_barrier
	s_waitcnt lgkmcnt(0)
	v_mfma_f32_16x16x32_bf16 v[30:33], v[130:133], v[190:193], 0
	v_mfma_f32_16x16x32_bf16 v[30:33], v[162:165], v[194:197], v[30:33]
	v_mfma_f32_16x16x32_bf16 v[26:29], v[166:169], v[190:193], 0
	v_mfma_f32_16x16x32_bf16 v[26:29], v[170:173], v[194:197], v[26:29]
	v_mfma_f32_16x16x32_bf16 v[22:25], v[130:133], v[198:201], 0
	v_mfma_f32_16x16x32_bf16 v[22:25], v[162:165], v[202:205], v[22:25]
	v_mfma_f32_16x16x32_bf16 v[18:21], v[166:169], v[198:201], 0
	v_mfma_f32_16x16x32_bf16 v[18:21], v[170:173], v[202:205], v[18:21]
	v_mfma_f32_16x16x32_bf16 v[14:17], v[130:133], v[206:209], 0
	v_mfma_f32_16x16x32_bf16 v[14:17], v[162:165], v[210:213], v[14:17]
	v_mfma_f32_16x16x32_bf16 v[10:13], v[166:169], v[206:209], 0
	v_mfma_f32_16x16x32_bf16 v[10:13], v[170:173], v[210:213], v[10:13]
	v_mfma_f32_16x16x32_bf16 v[6:9], v[130:133], v[214:217], 0
	v_mfma_f32_16x16x32_bf16 v[6:9], v[162:165], v[218:221], v[6:9]
	v_mfma_f32_16x16x32_bf16 v[2:5], v[166:169], v[214:217], 0
	v_mfma_f32_16x16x32_bf16 v[2:5], v[170:173], v[218:221], v[2:5]
	v_mfma_f32_16x16x32_bf16 v[94:97], v[174:177], v[190:193], 0
	v_mfma_f32_16x16x32_bf16 v[94:97], v[178:181], v[194:197], v[94:97]
	v_mfma_f32_16x16x32_bf16 v[90:93], v[182:185], v[190:193], 0
	v_mfma_f32_16x16x32_bf16 v[90:93], v[186:189], v[194:197], v[90:93]
	v_mfma_f32_16x16x32_bf16 v[86:89], v[174:177], v[198:201], 0
	v_mfma_f32_16x16x32_bf16 v[86:89], v[178:181], v[202:205], v[86:89]
	v_mfma_f32_16x16x32_bf16 v[82:85], v[182:185], v[198:201], 0
	v_mfma_f32_16x16x32_bf16 v[82:85], v[186:189], v[202:205], v[82:85]
	v_mfma_f32_16x16x32_bf16 v[78:81], v[174:177], v[206:209], 0
	v_mfma_f32_16x16x32_bf16 v[78:81], v[178:181], v[210:213], v[78:81]
	v_mfma_f32_16x16x32_bf16 v[74:77], v[182:185], v[206:209], 0
	v_mfma_f32_16x16x32_bf16 v[74:77], v[186:189], v[210:213], v[74:77]
	v_mfma_f32_16x16x32_bf16 v[70:73], v[174:177], v[214:217], 0
	v_mfma_f32_16x16x32_bf16 v[70:73], v[178:181], v[218:221], v[70:73]
	v_mfma_f32_16x16x32_bf16 v[66:69], v[182:185], v[214:217], 0
	v_mfma_f32_16x16x32_bf16 v[66:69], v[186:189], v[218:221], v[66:69]
	s_barrier
	s_add_i32 s47, 0, 0x18000
	v_add_u32_e32 v154, s47, v156
	s_add_i32 s48, 0, 0x1c000
	ds_read_b128 v[130:133], v154
	ds_read_b128 v[162:165], v154 offset:1024
	ds_read_b128 v[166:169], v154 offset:2048
	ds_read_b128 v[170:173], v154 offset:3072
	v_add_u32_e32 v154, s48, v156
	ds_read_b128 v[174:177], v154
	ds_read_b128 v[178:181], v154 offset:1024
	ds_read_b128 v[182:185], v154 offset:2048
	ds_read_b128 v[186:189], v154 offset:3072
	s_add_u32 s26, s26, 0x100000
	s_addc_u32 s27, s27, 0
	s_mov_b32 m0, s31
	ds_read_b128 v[190:193], v160 offset:32768
	ds_read_b128 v[194:197], v160 offset:33792
	ds_read_b128 v[198:201], v160 offset:34816
	ds_read_b128 v[202:205], v160 offset:35840
	ds_read_b128 v[206:209], v160 offset:36864
	ds_read_b128 v[210:213], v160 offset:37888
	ds_read_b128 v[214:217], v160 offset:38912
	ds_read_b128 v[218:221], v160 offset:39936
	global_load_lds_dwordx4 v140, s[26:27]
	s_mov_b32 m0, s33
	s_nop 0
	global_load_lds_dwordx4 v136, s[26:27]
	s_waitcnt vmcnt(8)
	s_waitcnt lgkmcnt(0)
	s_barrier
	s_waitcnt lgkmcnt(0)
	v_mfma_f32_16x16x32_bf16 v[62:65], v[130:133], v[190:193], v[62:65]
	v_mfma_f32_16x16x32_bf16 v[62:65], v[162:165], v[194:197], v[62:65]
	v_mfma_f32_16x16x32_bf16 v[58:61], v[166:169], v[190:193], v[58:61]
	v_mfma_f32_16x16x32_bf16 v[58:61], v[170:173], v[194:197], v[58:61]
	v_mfma_f32_16x16x32_bf16 v[54:57], v[130:133], v[198:201], v[54:57]
	v_mfma_f32_16x16x32_bf16 v[54:57], v[162:165], v[202:205], v[54:57]
	v_mfma_f32_16x16x32_bf16 v[50:53], v[166:169], v[198:201], v[50:53]
	v_mfma_f32_16x16x32_bf16 v[50:53], v[170:173], v[202:205], v[50:53]
	v_mfma_f32_16x16x32_bf16 v[46:49], v[130:133], v[206:209], v[46:49]
	v_mfma_f32_16x16x32_bf16 v[46:49], v[162:165], v[210:213], v[46:49]
	v_mfma_f32_16x16x32_bf16 v[42:45], v[166:169], v[206:209], v[42:45]
	v_mfma_f32_16x16x32_bf16 v[42:45], v[170:173], v[210:213], v[42:45]
	v_mfma_f32_16x16x32_bf16 v[38:41], v[130:133], v[214:217], v[38:41]
	v_mfma_f32_16x16x32_bf16 v[38:41], v[162:165], v[218:221], v[38:41]
	v_mfma_f32_16x16x32_bf16 v[34:37], v[166:169], v[214:217], v[34:37]
	v_mfma_f32_16x16x32_bf16 v[34:37], v[170:173], v[218:221], v[34:37]
	v_mfma_f32_16x16x32_bf16 v[126:129], v[174:177], v[190:193], v[126:129]
	v_mfma_f32_16x16x32_bf16 v[126:129], v[178:181], v[194:197], v[126:129]
	v_mfma_f32_16x16x32_bf16 v[122:125], v[182:185], v[190:193], v[122:125]
	v_mfma_f32_16x16x32_bf16 v[122:125], v[186:189], v[194:197], v[122:125]
	v_mfma_f32_16x16x32_bf16 v[118:121], v[174:177], v[198:201], v[118:121]
	v_mfma_f32_16x16x32_bf16 v[118:121], v[178:181], v[202:205], v[118:121]
	v_mfma_f32_16x16x32_bf16 v[114:117], v[182:185], v[198:201], v[114:117]
	v_mfma_f32_16x16x32_bf16 v[114:117], v[186:189], v[202:205], v[114:117]
	v_mfma_f32_16x16x32_bf16 v[110:113], v[174:177], v[206:209], v[110:113]
	v_mfma_f32_16x16x32_bf16 v[110:113], v[178:181], v[210:213], v[110:113]
	v_mfma_f32_16x16x32_bf16 v[106:109], v[182:185], v[206:209], v[106:109]
	v_mfma_f32_16x16x32_bf16 v[106:109], v[186:189], v[210:213], v[106:109]
	v_mfma_f32_16x16x32_bf16 v[102:105], v[174:177], v[214:217], v[102:105]
	v_mfma_f32_16x16x32_bf16 v[102:105], v[178:181], v[218:221], v[102:105]
	v_mfma_f32_16x16x32_bf16 v[98:101], v[182:185], v[214:217], v[98:101]
	v_mfma_f32_16x16x32_bf16 v[98:101], v[186:189], v[218:221], v[98:101]
	s_barrier
	s_add_u32 s26, s24, 0x4000
	s_addc_u32 s27, s25, 0
	s_add_i32 s47, s47, s28
	s_mov_b32 m0, s47
	ds_read_b128 v[190:193], v160 offset:49152
	ds_read_b128 v[194:197], v160 offset:50176
	ds_read_b128 v[198:201], v160 offset:51200
	ds_read_b128 v[202:205], v160 offset:52224
	ds_read_b128 v[206:209], v160 offset:53248
	ds_read_b128 v[210:213], v160 offset:54272
	ds_read_b128 v[214:217], v160 offset:55296
	ds_read_b128 v[218:221], v160 offset:56320
	global_load_lds_dwordx4 v138, s[26:27]
	s_add_i32 m0, s47, 0x2000
	s_add_u32 s24, s24, 0x104000
	s_addc_u32 s25, s25, 0
	global_load_lds_dwordx4 v134, s[26:27]
	s_add_i32 s26, s48, s28
	s_mov_b32 m0, s26
	s_nop 0
	global_load_lds_dwordx4 v138, s[24:25]
	s_add_i32 m0, s26, 0x2000
	s_nop 0
	global_load_lds_dwordx4 v134, s[24:25]
	s_mov_b32 m0, s34
	s_nop 0
	global_load_lds_dwordx4 v140, s[22:23]
	s_mov_b32 m0, s35
	s_nop 0
	global_load_lds_dwordx4 v136, s[22:23]
	s_waitcnt vmcnt(8)
	s_waitcnt lgkmcnt(0)
	s_barrier
	s_waitcnt lgkmcnt(0)
	v_mfma_f32_16x16x32_bf16 v[30:33], v[130:133], v[190:193], v[30:33]
	v_mfma_f32_16x16x32_bf16 v[30:33], v[162:165], v[194:197], v[30:33]
	v_mfma_f32_16x16x32_bf16 v[26:29], v[166:169], v[190:193], v[26:29]
	v_mfma_f32_16x16x32_bf16 v[26:29], v[170:173], v[194:197], v[26:29]
	v_mfma_f32_16x16x32_bf16 v[22:25], v[130:133], v[198:201], v[22:25]
	v_mfma_f32_16x16x32_bf16 v[22:25], v[162:165], v[202:205], v[22:25]
	v_mfma_f32_16x16x32_bf16 v[18:21], v[166:169], v[198:201], v[18:21]
	v_mfma_f32_16x16x32_bf16 v[18:21], v[170:173], v[202:205], v[18:21]
	v_mfma_f32_16x16x32_bf16 v[14:17], v[130:133], v[206:209], v[14:17]
	v_mfma_f32_16x16x32_bf16 v[14:17], v[162:165], v[210:213], v[14:17]
	v_mfma_f32_16x16x32_bf16 v[10:13], v[166:169], v[206:209], v[10:13]
	v_mfma_f32_16x16x32_bf16 v[10:13], v[170:173], v[210:213], v[10:13]
	v_mfma_f32_16x16x32_bf16 v[6:9], v[130:133], v[214:217], v[6:9]
	v_mfma_f32_16x16x32_bf16 v[6:9], v[162:165], v[218:221], v[6:9]
	v_mfma_f32_16x16x32_bf16 v[2:5], v[166:169], v[214:217], v[2:5]
	v_mfma_f32_16x16x32_bf16 v[2:5], v[170:173], v[218:221], v[2:5]
	v_mfma_f32_16x16x32_bf16 v[94:97], v[174:177], v[190:193], v[94:97]
	v_mfma_f32_16x16x32_bf16 v[94:97], v[178:181], v[194:197], v[94:97]
	v_mfma_f32_16x16x32_bf16 v[90:93], v[182:185], v[190:193], v[90:93]
	v_mfma_f32_16x16x32_bf16 v[90:93], v[186:189], v[194:197], v[90:93]
	v_mfma_f32_16x16x32_bf16 v[86:89], v[174:177], v[198:201], v[86:89]
	v_mfma_f32_16x16x32_bf16 v[86:89], v[178:181], v[202:205], v[86:89]
	v_mfma_f32_16x16x32_bf16 v[82:85], v[182:185], v[198:201], v[82:85]
	v_mfma_f32_16x16x32_bf16 v[82:85], v[186:189], v[202:205], v[82:85]
	v_mfma_f32_16x16x32_bf16 v[78:81], v[174:177], v[206:209], v[78:81]
	v_mfma_f32_16x16x32_bf16 v[78:81], v[178:181], v[210:213], v[78:81]
	v_mfma_f32_16x16x32_bf16 v[74:77], v[182:185], v[206:209], v[74:77]
	v_mfma_f32_16x16x32_bf16 v[74:77], v[186:189], v[210:213], v[74:77]
	v_mfma_f32_16x16x32_bf16 v[70:73], v[174:177], v[214:217], v[70:73]
	v_mfma_f32_16x16x32_bf16 v[70:73], v[178:181], v[218:221], v[70:73]
	v_mfma_f32_16x16x32_bf16 v[66:69], v[182:185], v[214:217], v[66:69]
	v_mfma_f32_16x16x32_bf16 v[66:69], v[186:189], v[218:221], v[66:69]
	s_barrier
	s_add_i32 s46, s46, 2
	s_add_u32 s20, s20, 0x8000
	s_addc_u32 s21, s21, 0
	s_add_u32 s44, s44, 0x8000
	s_addc_u32 s45, s45, 0
	s_cmp_gt_u32 s46, 61

.LBB0_375:
	s_ashr_i32 s21, s20, 31
	s_lshl_b64 s[22:23], s[20:21], 21
	v_readlane_b32 s24, v251, 17
	v_readlane_b32 s25, v251, 18
	s_add_u32 s22, s24, s22
	s_addc_u32 s23, s25, s23
	s_and_b64 s[24:25], s[2:3], exec
	s_cselect_b32 s21, s23, s27
	s_cselect_b32 s80, s22, s26
	s_ashr_i32 s19, s18, 31
	s_lshl_b64 s[24:25], s[18:19], 21
	s_add_u32 s24, s42, s24
	s_addc_u32 s25, s43, s25
	s_and_b64 s[36:37], s[2:3], exec
	s_cselect_b32 s19, s25, s35
	s_cselect_b32 s81, s24, s34
	s_add_u32 s26, s26, 0x104000
	s_addc_u32 s27, s27, 0
	s_add_u32 s83, s34, 0x8000
	s_addc_u32 s86, s35, 0
	s_mov_b32 s87, -2
	ds_read_b128 v[130:133], v159
	ds_read_b128 v[162:165], v159 offset:1024
	ds_read_b128 v[166:169], v159 offset:2048
	ds_read_b128 v[170:173], v159 offset:3072
	ds_read_b128 v[174:177], v160
	ds_read_b128 v[178:181], v160 offset:1024
	ds_read_b128 v[182:185], v160 offset:2048
	ds_read_b128 v[186:189], v160 offset:3072
	s_add_u32 s34, s26, 0xfff04000
	s_addc_u32 s35, s27, -1
	s_cmp_eq_u32 s87, 60
	s_cselect_b32 s38, s80, s34
	s_cselect_b32 s39, s21, s35
	s_cselect_b32 s36, s81, s83
	s_cselect_b32 s37, s19, s86
	s_add_u32 s34, s38, 0x4000
	s_addc_u32 s35, s39, 0
	s_add_i32 m0, s46, 0xc000
	ds_read_b128 v[190:193], v161
	ds_read_b128 v[194:197], v161 offset:1024
	ds_read_b128 v[198:201], v161 offset:2048
	ds_read_b128 v[202:205], v161 offset:3072
	ds_read_b128 v[206:209], v161 offset:4096
	ds_read_b128 v[210:213], v161 offset:5120
	ds_read_b128 v[214:217], v161 offset:6144
	ds_read_b128 v[218:221], v161 offset:7168
	global_load_lds_dwordx4 v146, s[26:27]
	s_add_i32 m0, s46, 0xe000
	s_nop 0
	global_load_lds_dwordx4 v148, s[26:27]
	s_waitcnt vmcnt(8)
	s_waitcnt lgkmcnt(0)
	s_barrier
	s_waitcnt lgkmcnt(0)
	v_mfma_f32_16x16x32_bf16 v[62:65], v[130:133], v[190:193], 0
	v_mfma_f32_16x16x32_bf16 v[62:65], v[162:165], v[194:197], v[62:65]
	v_mfma_f32_16x16x32_bf16 v[58:61], v[166:169], v[190:193], 0
	v_mfma_f32_16x16x32_bf16 v[58:61], v[170:173], v[194:197], v[58:61]
	v_mfma_f32_16x16x32_bf16 v[54:57], v[130:133], v[198:201], 0
	v_mfma_f32_16x16x32_bf16 v[54:57], v[162:165], v[202:205], v[54:57]
	v_mfma_f32_16x16x32_bf16 v[50:53], v[166:169], v[198:201], 0
	v_mfma_f32_16x16x32_bf16 v[50:53], v[170:173], v[202:205], v[50:53]
	v_mfma_f32_16x16x32_bf16 v[46:49], v[130:133], v[206:209], 0
	v_mfma_f32_16x16x32_bf16 v[46:49], v[162:165], v[210:213], v[46:49]
	v_mfma_f32_16x16x32_bf16 v[42:45], v[166:169], v[206:209], 0
	v_mfma_f32_16x16x32_bf16 v[42:45], v[170:173], v[210:213], v[42:45]
	v_mfma_f32_16x16x32_bf16 v[38:41], v[130:133], v[214:217], 0
	v_mfma_f32_16x16x32_bf16 v[38:41], v[162:165], v[218:221], v[38:41]
	v_mfma_f32_16x16x32_bf16 v[34:37], v[166:169], v[214:217], 0
	v_mfma_f32_16x16x32_bf16 v[34:37], v[170:173], v[218:221], v[34:37]
	v_mfma_f32_16x16x32_bf16 v[126:129], v[174:177], v[190:193], 0
	v_mfma_f32_16x16x32_bf16 v[126:129], v[178:181], v[194:197], v[126:129]
	v_mfma_f32_16x16x32_bf16 v[122:125], v[182:185], v[190:193], 0
	v_mfma_f32_16x16x32_bf16 v[122:125], v[186:189], v[194:197], v[122:125]
	v_mfma_f32_16x16x32_bf16 v[118:121], v[174:177], v[198:201], 0
	v_mfma_f32_16x16x32_bf16 v[118:121], v[178:181], v[202:205], v[118:121]
	v_mfma_f32_16x16x32_bf16 v[114:117], v[182:185], v[198:201], 0
	v_mfma_f32_16x16x32_bf16 v[114:117], v[186:189], v[202:205], v[114:117]
	v_mfma_f32_16x16x32_bf16 v[110:113], v[174:177], v[206:209], 0
	v_mfma_f32_16x16x32_bf16 v[110:113], v[178:181], v[210:213], v[110:113]
	v_mfma_f32_16x16x32_bf16 v[106:109], v[182:185], v[206:209], 0
	v_mfma_f32_16x16x32_bf16 v[106:109], v[186:189], v[210:213], v[106:109]
	v_mfma_f32_16x16x32_bf16 v[102:105], v[174:177], v[214:217], 0
	v_mfma_f32_16x16x32_bf16 v[102:105], v[178:181], v[218:221], v[102:105]
	v_mfma_f32_16x16x32_bf16 v[98:101], v[182:185], v[214:217], 0
	v_mfma_f32_16x16x32_bf16 v[98:101], v[186:189], v[218:221], v[98:101]
	s_barrier
	s_add_i32 s88, s66, s41
	s_mov_b32 m0, s88
	ds_read_b128 v[190:193], v161 offset:16384
	ds_read_b128 v[194:197], v161 offset:17408
	ds_read_b128 v[198:201], v161 offset:18432
	ds_read_b128 v[202:205], v161 offset:19456
	ds_read_b128 v[206:209], v161 offset:20480
	ds_read_b128 v[210:213], v161 offset:21504
	ds_read_b128 v[214:217], v161 offset:22528
	ds_read_b128 v[218:221], v161 offset:23552
	global_load_lds_dwordx4 v138, s[36:37]
	s_add_i32 m0, s88, 0x2000
	s_add_u32 s88, s36, 0x100000
	s_addc_u32 s89, s37, 0
	s_add_i32 vcc_lo, s67, s41
	global_load_lds_dwordx4 v134, s[36:37]
	s_mov_b32 m0, vcc_lo
	s_nop 0
	global_load_lds_dwordx4 v138, s[88:89]
	s_add_i32 m0, vcc_lo, 0x2000
	s_nop 0
	global_load_lds_dwordx4 v134, s[88:89]
	s_mov_b32 m0, s46
	s_nop 0
	global_load_lds_dwordx4 v140, s[38:39]
	s_mov_b32 m0, s47
	s_nop 0
	global_load_lds_dwordx4 v136, s[38:39]
	s_waitcnt vmcnt(8)
	s_waitcnt lgkmcnt(0)
	s_barrier
	s_waitcnt lgkmcnt(0)
	v_mfma_f32_16x16x32_bf16 v[30:33], v[130:133], v[190:193], 0
	v_mfma_f32_16x16x32_bf16 v[30:33], v[162:165], v[194:197], v[30:33]
	v_mfma_f32_16x16x32_bf16 v[26:29], v[166:169], v[190:193], 0
	v_mfma_f32_16x16x32_bf16 v[26:29], v[170:173], v[194:197], v[26:29]
	v_mfma_f32_16x16x32_bf16 v[22:25], v[130:133], v[198:201], 0
	v_mfma_f32_16x16x32_bf16 v[22:25], v[162:165], v[202:205], v[22:25]
	v_mfma_f32_16x16x32_bf16 v[18:21], v[166:169], v[198:201], 0
	v_mfma_f32_16x16x32_bf16 v[18:21], v[170:173], v[202:205], v[18:21]
	v_mfma_f32_16x16x32_bf16 v[14:17], v[130:133], v[206:209], 0
	v_mfma_f32_16x16x32_bf16 v[14:17], v[162:165], v[210:213], v[14:17]
	v_mfma_f32_16x16x32_bf16 v[10:13], v[166:169], v[206:209], 0
	v_mfma_f32_16x16x32_bf16 v[10:13], v[170:173], v[210:213], v[10:13]
	v_mfma_f32_16x16x32_bf16 v[6:9], v[130:133], v[214:217], 0
	v_mfma_f32_16x16x32_bf16 v[6:9], v[162:165], v[218:221], v[6:9]
	v_mfma_f32_16x16x32_bf16 v[2:5], v[166:169], v[214:217], 0
	v_mfma_f32_16x16x32_bf16 v[2:5], v[170:173], v[218:221], v[2:5]
	v_mfma_f32_16x16x32_bf16 v[94:97], v[174:177], v[190:193], 0
	v_mfma_f32_16x16x32_bf16 v[94:97], v[178:181], v[194:197], v[94:97]
	v_mfma_f32_16x16x32_bf16 v[90:93], v[182:185], v[190:193], 0
	v_mfma_f32_16x16x32_bf16 v[90:93], v[186:189], v[194:197], v[90:93]
	v_mfma_f32_16x16x32_bf16 v[86:89], v[174:177], v[198:201], 0
	v_mfma_f32_16x16x32_bf16 v[86:89], v[178:181], v[202:205], v[86:89]
	v_mfma_f32_16x16x32_bf16 v[82:85], v[182:185], v[198:201], 0
	v_mfma_f32_16x16x32_bf16 v[82:85], v[186:189], v[202:205], v[82:85]
	v_mfma_f32_16x16x32_bf16 v[78:81], v[174:177], v[206:209], 0
	v_mfma_f32_16x16x32_bf16 v[78:81], v[178:181], v[210:213], v[78:81]
	v_mfma_f32_16x16x32_bf16 v[74:77], v[182:185], v[206:209], 0
	v_mfma_f32_16x16x32_bf16 v[74:77], v[186:189], v[210:213], v[74:77]
	v_mfma_f32_16x16x32_bf16 v[70:73], v[174:177], v[214:217], 0
	v_mfma_f32_16x16x32_bf16 v[70:73], v[178:181], v[218:221], v[70:73]
	v_mfma_f32_16x16x32_bf16 v[66:69], v[182:185], v[214:217], 0
	v_mfma_f32_16x16x32_bf16 v[66:69], v[186:189], v[218:221], v[66:69]
	s_barrier
	s_add_i32 s88, 0, 0x18000
	v_add_u32_e32 v154, s88, v157
	s_add_i32 s89, 0, 0x1c000
	ds_read_b128 v[130:133], v154
	ds_read_b128 v[162:165], v154 offset:1024
	ds_read_b128 v[166:169], v154 offset:2048
	ds_read_b128 v[170:173], v154 offset:3072
	v_add_u32_e32 v154, s89, v157
	ds_read_b128 v[174:177], v154
	ds_read_b128 v[178:181], v154 offset:1024
	ds_read_b128 v[182:185], v154 offset:2048
	ds_read_b128 v[186:189], v154 offset:3072
	s_add_u32 s38, s38, 0x100000
	s_addc_u32 s39, s39, 0
	s_mov_b32 m0, s58
	ds_read_b128 v[190:193], v161 offset:32768
	ds_read_b128 v[194:197], v161 offset:33792
	ds_read_b128 v[198:201], v161 offset:34816
	ds_read_b128 v[202:205], v161 offset:35840
	ds_read_b128 v[206:209], v161 offset:36864
	ds_read_b128 v[210:213], v161 offset:37888
	ds_read_b128 v[214:217], v161 offset:38912
	ds_read_b128 v[218:221], v161 offset:39936
	global_load_lds_dwordx4 v140, s[38:39]
	s_mov_b32 m0, s59
	s_nop 0
	global_load_lds_dwordx4 v136, s[38:39]
	s_waitcnt vmcnt(8)
	s_waitcnt lgkmcnt(0)
	s_barrier
	s_waitcnt lgkmcnt(0)
	v_mfma_f32_16x16x32_bf16 v[62:65], v[130:133], v[190:193], v[62:65]
	v_mfma_f32_16x16x32_bf16 v[62:65], v[162:165], v[194:197], v[62:65]
	v_mfma_f32_16x16x32_bf16 v[58:61], v[166:169], v[190:193], v[58:61]
	v_mfma_f32_16x16x32_bf16 v[58:61], v[170:173], v[194:197], v[58:61]
	v_mfma_f32_16x16x32_bf16 v[54:57], v[130:133], v[198:201], v[54:57]
	v_mfma_f32_16x16x32_bf16 v[54:57], v[162:165], v[202:205], v[54:57]
	v_mfma_f32_16x16x32_bf16 v[50:53], v[166:169], v[198:201], v[50:53]
	v_mfma_f32_16x16x32_bf16 v[50:53], v[170:173], v[202:205], v[50:53]
	v_mfma_f32_16x16x32_bf16 v[46:49], v[130:133], v[206:209], v[46:49]
	v_mfma_f32_16x16x32_bf16 v[46:49], v[162:165], v[210:213], v[46:49]
	v_mfma_f32_16x16x32_bf16 v[42:45], v[166:169], v[206:209], v[42:45]
	v_mfma_f32_16x16x32_bf16 v[42:45], v[170:173], v[210:213], v[42:45]
	v_mfma_f32_16x16x32_bf16 v[38:41], v[130:133], v[214:217], v[38:41]
	v_mfma_f32_16x16x32_bf16 v[38:41], v[162:165], v[218:221], v[38:41]
	v_mfma_f32_16x16x32_bf16 v[34:37], v[166:169], v[214:217], v[34:37]
	v_mfma_f32_16x16x32_bf16 v[34:37], v[170:173], v[218:221], v[34:37]
	v_mfma_f32_16x16x32_bf16 v[126:129], v[174:177], v[190:193], v[126:129]
	v_mfma_f32_16x16x32_bf16 v[126:129], v[178:181], v[194:197], v[126:129]
	v_mfma_f32_16x16x32_bf16 v[122:125], v[182:185], v[190:193], v[122:125]
	v_mfma_f32_16x16x32_bf16 v[122:125], v[186:189], v[194:197], v[122:125]
	v_mfma_f32_16x16x32_bf16 v[118:121], v[174:177], v[198:201], v[118:121]
	v_mfma_f32_16x16x32_bf16 v[118:121], v[178:181], v[202:205], v[118:121]
	v_mfma_f32_16x16x32_bf16 v[114:117], v[182:185], v[198:201], v[114:117]
	v_mfma_f32_16x16x32_bf16 v[114:117], v[186:189], v[202:205], v[114:117]
	v_mfma_f32_16x16x32_bf16 v[110:113], v[174:177], v[206:209], v[110:113]
	v_mfma_f32_16x16x32_bf16 v[110:113], v[178:181], v[210:213], v[110:113]
	v_mfma_f32_16x16x32_bf16 v[106:109], v[182:185], v[206:209], v[106:109]
	v_mfma_f32_16x16x32_bf16 v[106:109], v[186:189], v[210:213], v[106:109]
	v_mfma_f32_16x16x32_bf16 v[102:105], v[174:177], v[214:217], v[102:105]
	v_mfma_f32_16x16x32_bf16 v[102:105], v[178:181], v[218:221], v[102:105]
	v_mfma_f32_16x16x32_bf16 v[98:101], v[182:185], v[214:217], v[98:101]
	v_mfma_f32_16x16x32_bf16 v[98:101], v[186:189], v[218:221], v[98:101]
	s_barrier
	s_add_u32 s38, s36, 0x4000
	s_addc_u32 s39, s37, 0
	s_add_i32 s88, s88, s41
	s_mov_b32 m0, s88
	ds_read_b128 v[190:193], v161 offset:49152
	ds_read_b128 v[194:197], v161 offset:50176
	ds_read_b128 v[198:201], v161 offset:51200
	ds_read_b128 v[202:205], v161 offset:52224
	ds_read_b128 v[206:209], v161 offset:53248
	ds_read_b128 v[210:213], v161 offset:54272
	ds_read_b128 v[214:217], v161 offset:55296
	ds_read_b128 v[218:221], v161 offset:56320
	global_load_lds_dwordx4 v138, s[38:39]
	s_add_i32 m0, s88, 0x2000
	s_add_u32 s36, s36, 0x104000
	s_addc_u32 s37, s37, 0
	global_load_lds_dwordx4 v134, s[38:39]
	s_add_i32 s38, s89, s41
	s_mov_b32 m0, s38
	s_nop 0
	global_load_lds_dwordx4 v138, s[36:37]
	s_add_i32 m0, s38, 0x2000
	s_nop 0
	global_load_lds_dwordx4 v134, s[36:37]
	s_mov_b32 m0, s64
	s_nop 0
	global_load_lds_dwordx4 v140, s[34:35]
	s_mov_b32 m0, s65
	s_nop 0
	global_load_lds_dwordx4 v136, s[34:35]
	s_waitcnt vmcnt(8)
	s_waitcnt lgkmcnt(0)
	s_barrier
	s_waitcnt lgkmcnt(0)
	v_mfma_f32_16x16x32_bf16 v[30:33], v[130:133], v[190:193], v[30:33]
	v_mfma_f32_16x16x32_bf16 v[30:33], v[162:165], v[194:197], v[30:33]
	v_mfma_f32_16x16x32_bf16 v[26:29], v[166:169], v[190:193], v[26:29]
	v_mfma_f32_16x16x32_bf16 v[26:29], v[170:173], v[194:197], v[26:29]
	v_mfma_f32_16x16x32_bf16 v[22:25], v[130:133], v[198:201], v[22:25]
	v_mfma_f32_16x16x32_bf16 v[22:25], v[162:165], v[202:205], v[22:25]
	v_mfma_f32_16x16x32_bf16 v[18:21], v[166:169], v[198:201], v[18:21]
	v_mfma_f32_16x16x32_bf16 v[18:21], v[170:173], v[202:205], v[18:21]
	v_mfma_f32_16x16x32_bf16 v[14:17], v[130:133], v[206:209], v[14:17]
	v_mfma_f32_16x16x32_bf16 v[14:17], v[162:165], v[210:213], v[14:17]
	v_mfma_f32_16x16x32_bf16 v[10:13], v[166:169], v[206:209], v[10:13]
	v_mfma_f32_16x16x32_bf16 v[10:13], v[170:173], v[210:213], v[10:13]
	v_mfma_f32_16x16x32_bf16 v[6:9], v[130:133], v[214:217], v[6:9]
	v_mfma_f32_16x16x32_bf16 v[6:9], v[162:165], v[218:221], v[6:9]
	v_mfma_f32_16x16x32_bf16 v[2:5], v[166:169], v[214:217], v[2:5]
	v_mfma_f32_16x16x32_bf16 v[2:5], v[170:173], v[218:221], v[2:5]
	v_mfma_f32_16x16x32_bf16 v[94:97], v[174:177], v[190:193], v[94:97]
	v_mfma_f32_16x16x32_bf16 v[94:97], v[178:181], v[194:197], v[94:97]
	v_mfma_f32_16x16x32_bf16 v[90:93], v[182:185], v[190:193], v[90:93]
	v_mfma_f32_16x16x32_bf16 v[90:93], v[186:189], v[194:197], v[90:93]
	v_mfma_f32_16x16x32_bf16 v[86:89], v[174:177], v[198:201], v[86:89]
	v_mfma_f32_16x16x32_bf16 v[86:89], v[178:181], v[202:205], v[86:89]
	v_mfma_f32_16x16x32_bf16 v[82:85], v[182:185], v[198:201], v[82:85]
	v_mfma_f32_16x16x32_bf16 v[82:85], v[186:189], v[202:205], v[82:85]
	v_mfma_f32_16x16x32_bf16 v[78:81], v[174:177], v[206:209], v[78:81]
	v_mfma_f32_16x16x32_bf16 v[78:81], v[178:181], v[210:213], v[78:81]
	v_mfma_f32_16x16x32_bf16 v[74:77], v[182:185], v[206:209], v[74:77]
	v_mfma_f32_16x16x32_bf16 v[74:77], v[186:189], v[210:213], v[74:77]
	v_mfma_f32_16x16x32_bf16 v[70:73], v[174:177], v[214:217], v[70:73]
	v_mfma_f32_16x16x32_bf16 v[70:73], v[178:181], v[218:221], v[70:73]
	v_mfma_f32_16x16x32_bf16 v[66:69], v[182:185], v[214:217], v[66:69]
	v_mfma_f32_16x16x32_bf16 v[66:69], v[186:189], v[218:221], v[66:69]
	s_barrier
	s_add_i32 s87, s87, 2
	s_add_u32 s26, s26, 0x8000
	s_addc_u32 s27, s27, 0
	s_add_u32 s83, s83, 0x8000
	s_addc_u32 s86, s86, 0
	s_cmp_gt_u32 s87, 61

.LBB0_535:
	s_ashr_i32 s21, s20, 31
	s_lshl_b64 s[22:23], s[20:21], 21
	v_readlane_b32 s24, v251, 17
	v_readlane_b32 s25, v251, 18
	s_add_u32 s22, s24, s22
	s_addc_u32 s23, s25, s23
	s_and_b64 s[24:25], s[2:3], exec
	s_cselect_b32 s21, s23, s27
	s_cselect_b32 s74, s22, s26
	s_ashr_i32 s19, s18, 31
	s_lshl_b64 s[24:25], s[18:19], 21
	s_add_u32 s24, s39, s24
	s_addc_u32 s25, s40, s25
	s_and_b64 s[34:35], s[2:3], exec
	s_cselect_b32 s19, s25, s31
	s_cselect_b32 s75, s24, s30
	s_add_u32 s26, s26, 0x104000
	s_addc_u32 s27, s27, 0
	s_add_u32 s78, s30, 0x8000
	s_addc_u32 s79, s31, 0
	s_mov_b32 s80, -2
	ds_read_b128 v[130:133], v159
	ds_read_b128 v[162:165], v159 offset:1024
	ds_read_b128 v[166:169], v159 offset:2048
	ds_read_b128 v[170:173], v159 offset:3072
	ds_read_b128 v[174:177], v160
	ds_read_b128 v[178:181], v160 offset:1024
	ds_read_b128 v[182:185], v160 offset:2048
	ds_read_b128 v[186:189], v160 offset:3072
	s_add_u32 s30, s26, 0xfff04000
	s_addc_u32 s31, s27, -1
	s_cmp_eq_u32 s80, 60
	s_cselect_b32 s36, s74, s30
	s_cselect_b32 s37, s21, s31
	s_cselect_b32 s34, s75, s78
	s_cselect_b32 s35, s19, s79
	s_add_u32 s30, s36, 0x4000
	s_addc_u32 s31, s37, 0
	s_add_i32 m0, s42, 0xc000
	ds_read_b128 v[190:193], v161
	ds_read_b128 v[194:197], v161 offset:1024
	ds_read_b128 v[198:201], v161 offset:2048
	ds_read_b128 v[202:205], v161 offset:3072
	ds_read_b128 v[206:209], v161 offset:4096
	ds_read_b128 v[210:213], v161 offset:5120
	ds_read_b128 v[214:217], v161 offset:6144
	ds_read_b128 v[218:221], v161 offset:7168
	global_load_lds_dwordx4 v146, s[26:27]
	s_add_i32 m0, s42, 0xe000
	s_nop 0
	global_load_lds_dwordx4 v148, s[26:27]
	s_waitcnt vmcnt(8)
	s_waitcnt lgkmcnt(0)
	s_barrier
	s_waitcnt lgkmcnt(0)
	v_mfma_f32_16x16x32_bf16 v[62:65], v[130:133], v[190:193], 0
	v_mfma_f32_16x16x32_bf16 v[62:65], v[162:165], v[194:197], v[62:65]
	v_mfma_f32_16x16x32_bf16 v[58:61], v[166:169], v[190:193], 0
	v_mfma_f32_16x16x32_bf16 v[58:61], v[170:173], v[194:197], v[58:61]
	v_mfma_f32_16x16x32_bf16 v[54:57], v[130:133], v[198:201], 0
	v_mfma_f32_16x16x32_bf16 v[54:57], v[162:165], v[202:205], v[54:57]
	v_mfma_f32_16x16x32_bf16 v[50:53], v[166:169], v[198:201], 0
	v_mfma_f32_16x16x32_bf16 v[50:53], v[170:173], v[202:205], v[50:53]
	v_mfma_f32_16x16x32_bf16 v[46:49], v[130:133], v[206:209], 0
	v_mfma_f32_16x16x32_bf16 v[46:49], v[162:165], v[210:213], v[46:49]
	v_mfma_f32_16x16x32_bf16 v[42:45], v[166:169], v[206:209], 0
	v_mfma_f32_16x16x32_bf16 v[42:45], v[170:173], v[210:213], v[42:45]
	v_mfma_f32_16x16x32_bf16 v[38:41], v[130:133], v[214:217], 0
	v_mfma_f32_16x16x32_bf16 v[38:41], v[162:165], v[218:221], v[38:41]
	v_mfma_f32_16x16x32_bf16 v[34:37], v[166:169], v[214:217], 0
	v_mfma_f32_16x16x32_bf16 v[34:37], v[170:173], v[218:221], v[34:37]
	v_mfma_f32_16x16x32_bf16 v[126:129], v[174:177], v[190:193], 0
	v_mfma_f32_16x16x32_bf16 v[126:129], v[178:181], v[194:197], v[126:129]
	v_mfma_f32_16x16x32_bf16 v[122:125], v[182:185], v[190:193], 0
	v_mfma_f32_16x16x32_bf16 v[122:125], v[186:189], v[194:197], v[122:125]
	v_mfma_f32_16x16x32_bf16 v[118:121], v[174:177], v[198:201], 0
	v_mfma_f32_16x16x32_bf16 v[118:121], v[178:181], v[202:205], v[118:121]
	v_mfma_f32_16x16x32_bf16 v[114:117], v[182:185], v[198:201], 0
	v_mfma_f32_16x16x32_bf16 v[114:117], v[186:189], v[202:205], v[114:117]
	v_mfma_f32_16x16x32_bf16 v[110:113], v[174:177], v[206:209], 0
	v_mfma_f32_16x16x32_bf16 v[110:113], v[178:181], v[210:213], v[110:113]
	v_mfma_f32_16x16x32_bf16 v[106:109], v[182:185], v[206:209], 0
	v_mfma_f32_16x16x32_bf16 v[106:109], v[186:189], v[210:213], v[106:109]
	v_mfma_f32_16x16x32_bf16 v[102:105], v[174:177], v[214:217], 0
	v_mfma_f32_16x16x32_bf16 v[102:105], v[178:181], v[218:221], v[102:105]
	v_mfma_f32_16x16x32_bf16 v[98:101], v[182:185], v[214:217], 0
	v_mfma_f32_16x16x32_bf16 v[98:101], v[186:189], v[218:221], v[98:101]
	s_barrier
	s_add_i32 s81, s62, s38
	s_mov_b32 m0, s81
	ds_read_b128 v[190:193], v161 offset:16384
	ds_read_b128 v[194:197], v161 offset:17408
	ds_read_b128 v[198:201], v161 offset:18432
	ds_read_b128 v[202:205], v161 offset:19456
	ds_read_b128 v[206:209], v161 offset:20480
	ds_read_b128 v[210:213], v161 offset:21504
	ds_read_b128 v[214:217], v161 offset:22528
	ds_read_b128 v[218:221], v161 offset:23552
	global_load_lds_dwordx4 v138, s[34:35]
	s_add_i32 m0, s81, 0x2000
	s_add_u32 s86, s34, 0x100000
	s_addc_u32 s87, s35, 0
	s_add_i32 s81, s63, s38
	global_load_lds_dwordx4 v134, s[34:35]
	s_mov_b32 m0, s81
	s_nop 0
	global_load_lds_dwordx4 v138, s[86:87]
	s_add_i32 m0, s81, 0x2000
	s_nop 0
	global_load_lds_dwordx4 v134, s[86:87]
	s_mov_b32 m0, s42
	s_nop 0
	global_load_lds_dwordx4 v140, s[36:37]
	s_mov_b32 m0, s43
	s_nop 0
	global_load_lds_dwordx4 v136, s[36:37]
	s_waitcnt vmcnt(8)
	s_waitcnt lgkmcnt(0)
	s_barrier
	s_waitcnt lgkmcnt(0)
	v_mfma_f32_16x16x32_bf16 v[30:33], v[130:133], v[190:193], 0
	v_mfma_f32_16x16x32_bf16 v[30:33], v[162:165], v[194:197], v[30:33]
	v_mfma_f32_16x16x32_bf16 v[26:29], v[166:169], v[190:193], 0
	v_mfma_f32_16x16x32_bf16 v[26:29], v[170:173], v[194:197], v[26:29]
	v_mfma_f32_16x16x32_bf16 v[22:25], v[130:133], v[198:201], 0
	v_mfma_f32_16x16x32_bf16 v[22:25], v[162:165], v[202:205], v[22:25]
	v_mfma_f32_16x16x32_bf16 v[18:21], v[166:169], v[198:201], 0
	v_mfma_f32_16x16x32_bf16 v[18:21], v[170:173], v[202:205], v[18:21]
	v_mfma_f32_16x16x32_bf16 v[14:17], v[130:133], v[206:209], 0
	v_mfma_f32_16x16x32_bf16 v[14:17], v[162:165], v[210:213], v[14:17]
	v_mfma_f32_16x16x32_bf16 v[10:13], v[166:169], v[206:209], 0
	v_mfma_f32_16x16x32_bf16 v[10:13], v[170:173], v[210:213], v[10:13]
	v_mfma_f32_16x16x32_bf16 v[6:9], v[130:133], v[214:217], 0
	v_mfma_f32_16x16x32_bf16 v[6:9], v[162:165], v[218:221], v[6:9]
	v_mfma_f32_16x16x32_bf16 v[2:5], v[166:169], v[214:217], 0
	v_mfma_f32_16x16x32_bf16 v[2:5], v[170:173], v[218:221], v[2:5]
	v_mfma_f32_16x16x32_bf16 v[94:97], v[174:177], v[190:193], 0
	v_mfma_f32_16x16x32_bf16 v[94:97], v[178:181], v[194:197], v[94:97]
	v_mfma_f32_16x16x32_bf16 v[90:93], v[182:185], v[190:193], 0
	v_mfma_f32_16x16x32_bf16 v[90:93], v[186:189], v[194:197], v[90:93]
	v_mfma_f32_16x16x32_bf16 v[86:89], v[174:177], v[198:201], 0
	v_mfma_f32_16x16x32_bf16 v[86:89], v[178:181], v[202:205], v[86:89]
	v_mfma_f32_16x16x32_bf16 v[82:85], v[182:185], v[198:201], 0
	v_mfma_f32_16x16x32_bf16 v[82:85], v[186:189], v[202:205], v[82:85]
	v_mfma_f32_16x16x32_bf16 v[78:81], v[174:177], v[206:209], 0
	v_mfma_f32_16x16x32_bf16 v[78:81], v[178:181], v[210:213], v[78:81]
	v_mfma_f32_16x16x32_bf16 v[74:77], v[182:185], v[206:209], 0
	v_mfma_f32_16x16x32_bf16 v[74:77], v[186:189], v[210:213], v[74:77]
	v_mfma_f32_16x16x32_bf16 v[70:73], v[174:177], v[214:217], 0
	v_mfma_f32_16x16x32_bf16 v[70:73], v[178:181], v[218:221], v[70:73]
	v_mfma_f32_16x16x32_bf16 v[66:69], v[182:185], v[214:217], 0
	v_mfma_f32_16x16x32_bf16 v[66:69], v[186:189], v[218:221], v[66:69]
	s_barrier
	s_add_i32 s81, 0, 0x18000
	v_add_u32_e32 v154, s81, v157
	s_add_i32 s83, 0, 0x1c000
	ds_read_b128 v[130:133], v154
	ds_read_b128 v[162:165], v154 offset:1024
	ds_read_b128 v[166:169], v154 offset:2048
	ds_read_b128 v[170:173], v154 offset:3072
	v_add_u32_e32 v154, s83, v157
	ds_read_b128 v[174:177], v154
	ds_read_b128 v[178:181], v154 offset:1024
	ds_read_b128 v[182:185], v154 offset:2048
	ds_read_b128 v[186:189], v154 offset:3072
	s_add_u32 s36, s36, 0x100000
	s_addc_u32 s37, s37, 0
	s_mov_b32 m0, s46
	ds_read_b128 v[190:193], v161 offset:32768
	ds_read_b128 v[194:197], v161 offset:33792
	ds_read_b128 v[198:201], v161 offset:34816
	ds_read_b128 v[202:205], v161 offset:35840
	ds_read_b128 v[206:209], v161 offset:36864
	ds_read_b128 v[210:213], v161 offset:37888
	ds_read_b128 v[214:217], v161 offset:38912
	ds_read_b128 v[218:221], v161 offset:39936
	global_load_lds_dwordx4 v140, s[36:37]
	s_mov_b32 m0, s47
	s_nop 0
	global_load_lds_dwordx4 v136, s[36:37]
	s_waitcnt vmcnt(8)
	s_waitcnt lgkmcnt(0)
	s_barrier
	s_waitcnt lgkmcnt(0)
	v_mfma_f32_16x16x32_bf16 v[62:65], v[130:133], v[190:193], v[62:65]
	v_mfma_f32_16x16x32_bf16 v[62:65], v[162:165], v[194:197], v[62:65]
	v_mfma_f32_16x16x32_bf16 v[58:61], v[166:169], v[190:193], v[58:61]
	v_mfma_f32_16x16x32_bf16 v[58:61], v[170:173], v[194:197], v[58:61]
	v_mfma_f32_16x16x32_bf16 v[54:57], v[130:133], v[198:201], v[54:57]
	v_mfma_f32_16x16x32_bf16 v[54:57], v[162:165], v[202:205], v[54:57]
	v_mfma_f32_16x16x32_bf16 v[50:53], v[166:169], v[198:201], v[50:53]
	v_mfma_f32_16x16x32_bf16 v[50:53], v[170:173], v[202:205], v[50:53]
	v_mfma_f32_16x16x32_bf16 v[46:49], v[130:133], v[206:209], v[46:49]
	v_mfma_f32_16x16x32_bf16 v[46:49], v[162:165], v[210:213], v[46:49]
	v_mfma_f32_16x16x32_bf16 v[42:45], v[166:169], v[206:209], v[42:45]
	v_mfma_f32_16x16x32_bf16 v[42:45], v[170:173], v[210:213], v[42:45]
	v_mfma_f32_16x16x32_bf16 v[38:41], v[130:133], v[214:217], v[38:41]
	v_mfma_f32_16x16x32_bf16 v[38:41], v[162:165], v[218:221], v[38:41]
	v_mfma_f32_16x16x32_bf16 v[34:37], v[166:169], v[214:217], v[34:37]
	v_mfma_f32_16x16x32_bf16 v[34:37], v[170:173], v[218:221], v[34:37]
	v_mfma_f32_16x16x32_bf16 v[126:129], v[174:177], v[190:193], v[126:129]
	v_mfma_f32_16x16x32_bf16 v[126:129], v[178:181], v[194:197], v[126:129]
	v_mfma_f32_16x16x32_bf16 v[122:125], v[182:185], v[190:193], v[122:125]
	v_mfma_f32_16x16x32_bf16 v[122:125], v[186:189], v[194:197], v[122:125]
	v_mfma_f32_16x16x32_bf16 v[118:121], v[174:177], v[198:201], v[118:121]
	v_mfma_f32_16x16x32_bf16 v[118:121], v[178:181], v[202:205], v[118:121]
	v_mfma_f32_16x16x32_bf16 v[114:117], v[182:185], v[198:201], v[114:117]
	v_mfma_f32_16x16x32_bf16 v[114:117], v[186:189], v[202:205], v[114:117]
	v_mfma_f32_16x16x32_bf16 v[110:113], v[174:177], v[206:209], v[110:113]
	v_mfma_f32_16x16x32_bf16 v[110:113], v[178:181], v[210:213], v[110:113]
	v_mfma_f32_16x16x32_bf16 v[106:109], v[182:185], v[206:209], v[106:109]
	v_mfma_f32_16x16x32_bf16 v[106:109], v[186:189], v[210:213], v[106:109]
	v_mfma_f32_16x16x32_bf16 v[102:105], v[174:177], v[214:217], v[102:105]
	v_mfma_f32_16x16x32_bf16 v[102:105], v[178:181], v[218:221], v[102:105]
	v_mfma_f32_16x16x32_bf16 v[98:101], v[182:185], v[214:217], v[98:101]
	v_mfma_f32_16x16x32_bf16 v[98:101], v[186:189], v[218:221], v[98:101]
	s_barrier
	s_add_u32 s36, s34, 0x4000
	s_addc_u32 s37, s35, 0
	s_add_i32 s81, s81, s38
	s_mov_b32 m0, s81
	ds_read_b128 v[190:193], v161 offset:49152
	ds_read_b128 v[194:197], v161 offset:50176
	ds_read_b128 v[198:201], v161 offset:51200
	ds_read_b128 v[202:205], v161 offset:52224
	ds_read_b128 v[206:209], v161 offset:53248
	ds_read_b128 v[210:213], v161 offset:54272
	ds_read_b128 v[214:217], v161 offset:55296
	ds_read_b128 v[218:221], v161 offset:56320
	global_load_lds_dwordx4 v138, s[36:37]
	s_add_i32 m0, s81, 0x2000
	s_add_u32 s34, s34, 0x104000
	s_addc_u32 s35, s35, 0
	global_load_lds_dwordx4 v134, s[36:37]
	s_add_i32 s36, s83, s38
	s_mov_b32 m0, s36
	s_nop 0
	global_load_lds_dwordx4 v138, s[34:35]
	s_add_i32 m0, s36, 0x2000
	s_nop 0
	global_load_lds_dwordx4 v134, s[34:35]
	s_mov_b32 m0, s58
	s_nop 0
	global_load_lds_dwordx4 v140, s[30:31]
	s_mov_b32 m0, s59
	s_nop 0
	global_load_lds_dwordx4 v136, s[30:31]
	s_waitcnt vmcnt(8)
	s_waitcnt lgkmcnt(0)
	s_barrier
	s_waitcnt lgkmcnt(0)
	v_mfma_f32_16x16x32_bf16 v[30:33], v[130:133], v[190:193], v[30:33]
	v_mfma_f32_16x16x32_bf16 v[30:33], v[162:165], v[194:197], v[30:33]
	v_mfma_f32_16x16x32_bf16 v[26:29], v[166:169], v[190:193], v[26:29]
	v_mfma_f32_16x16x32_bf16 v[26:29], v[170:173], v[194:197], v[26:29]
	v_mfma_f32_16x16x32_bf16 v[22:25], v[130:133], v[198:201], v[22:25]
	v_mfma_f32_16x16x32_bf16 v[22:25], v[162:165], v[202:205], v[22:25]
	v_mfma_f32_16x16x32_bf16 v[18:21], v[166:169], v[198:201], v[18:21]
	v_mfma_f32_16x16x32_bf16 v[18:21], v[170:173], v[202:205], v[18:21]
	v_mfma_f32_16x16x32_bf16 v[14:17], v[130:133], v[206:209], v[14:17]
	v_mfma_f32_16x16x32_bf16 v[14:17], v[162:165], v[210:213], v[14:17]
	v_mfma_f32_16x16x32_bf16 v[10:13], v[166:169], v[206:209], v[10:13]
	v_mfma_f32_16x16x32_bf16 v[10:13], v[170:173], v[210:213], v[10:13]
	v_mfma_f32_16x16x32_bf16 v[6:9], v[130:133], v[214:217], v[6:9]
	v_mfma_f32_16x16x32_bf16 v[6:9], v[162:165], v[218:221], v[6:9]
	v_mfma_f32_16x16x32_bf16 v[2:5], v[166:169], v[214:217], v[2:5]
	v_mfma_f32_16x16x32_bf16 v[2:5], v[170:173], v[218:221], v[2:5]
	v_mfma_f32_16x16x32_bf16 v[94:97], v[174:177], v[190:193], v[94:97]
	v_mfma_f32_16x16x32_bf16 v[94:97], v[178:181], v[194:197], v[94:97]
	v_mfma_f32_16x16x32_bf16 v[90:93], v[182:185], v[190:193], v[90:93]
	v_mfma_f32_16x16x32_bf16 v[90:93], v[186:189], v[194:197], v[90:93]
	v_mfma_f32_16x16x32_bf16 v[86:89], v[174:177], v[198:201], v[86:89]
	v_mfma_f32_16x16x32_bf16 v[86:89], v[178:181], v[202:205], v[86:89]
	v_mfma_f32_16x16x32_bf16 v[82:85], v[182:185], v[198:201], v[82:85]
	v_mfma_f32_16x16x32_bf16 v[82:85], v[186:189], v[202:205], v[82:85]
	v_mfma_f32_16x16x32_bf16 v[78:81], v[174:177], v[206:209], v[78:81]
	v_mfma_f32_16x16x32_bf16 v[78:81], v[178:181], v[210:213], v[78:81]
	v_mfma_f32_16x16x32_bf16 v[74:77], v[182:185], v[206:209], v[74:77]
	v_mfma_f32_16x16x32_bf16 v[74:77], v[186:189], v[210:213], v[74:77]
	v_mfma_f32_16x16x32_bf16 v[70:73], v[174:177], v[214:217], v[70:73]
	v_mfma_f32_16x16x32_bf16 v[70:73], v[178:181], v[218:221], v[70:73]
	v_mfma_f32_16x16x32_bf16 v[66:69], v[182:185], v[214:217], v[66:69]
	v_mfma_f32_16x16x32_bf16 v[66:69], v[186:189], v[218:221], v[66:69]
	s_barrier
	s_add_i32 s80, s80, 2
	s_add_u32 s26, s26, 0x8000
	s_addc_u32 s27, s27, 0
	s_add_u32 s78, s78, 0x8000
	s_addc_u32 s79, s79, 0
	s_cmp_gt_u32 s80, 61

.LBB0_1087:
	s_ashr_i32 s25, s24, 31
	s_lshl_b64 s[26:27], s[24:25], 21
	s_add_u32 s26, s28, s26
	s_addc_u32 s27, s29, s27
	s_and_b64 s[30:31], s[6:7], exec
	s_cselect_b32 s25, s27, s37
	s_cselect_b32 s35, s26, s36
	s_ashr_i32 s23, s22, 31
	s_lshl_b64 s[30:31], s[22:23], 21
	s_add_u32 s30, s52, s30
	s_addc_u32 s31, s53, s31
	s_and_b64 s[40:41], s[6:7], exec
	s_cselect_b32 s23, s31, s39
	s_cselect_b32 s69, s30, s38
	s_add_u32 s36, s36, 0x104000
	s_addc_u32 s37, s37, 0
	s_add_u32 s70, s38, 0x8000
	s_addc_u32 s71, s39, 0
	s_mov_b32 s72, -2
	s_waitcnt lgkmcnt(0)
	ds_read_b128 v[130:133], v209
	ds_read_b128 v[134:137], v209 offset:1024
	ds_read_b128 v[138:141], v209 offset:2048
	ds_read_b128 v[142:145], v209 offset:3072
	ds_read_b128 v[146:149], v210
	ds_read_b128 v[150:153], v210 offset:1024
	ds_read_b128 v[154:157], v210 offset:2048
	ds_read_b128 v[158:161], v210 offset:3072
	s_add_u32 s38, s36, 0xfff04000
	s_addc_u32 s39, s37, -1
	s_cmp_eq_u32 s72, 60
	s_cselect_b32 s42, s35, s38
	s_cselect_b32 s43, s25, s39
	s_cselect_b32 s40, s69, s70
	s_cselect_b32 s41, s23, s71
	s_add_u32 s38, s42, 0x4000
	s_addc_u32 s39, s43, 0
	s_add_i32 m0, s47, 0xc000
	ds_read_b128 v[162:165], v211
	ds_read_b128 v[166:169], v211 offset:1024
	ds_read_b128 v[170:173], v211 offset:2048
	ds_read_b128 v[174:177], v211 offset:3072
	ds_read_b128 v[196:199], v211 offset:4096
	ds_read_b128 v[200:203], v211 offset:5120
	ds_read_b128 v[214:217], v211 offset:6144
	ds_read_b128 v[218:221], v211 offset:7168
	global_load_lds_dwordx4 v188, s[36:37]
	s_add_i32 m0, s47, 0xe000
	s_nop 0
	global_load_lds_dwordx4 v190, s[36:37]
	s_waitcnt vmcnt(8)
	s_waitcnt lgkmcnt(0)
	s_barrier
	s_waitcnt lgkmcnt(0)
	v_mfma_f32_16x16x32_bf16 v[126:129], v[130:133], v[162:165], 0
	v_mfma_f32_16x16x32_bf16 v[126:129], v[134:137], v[166:169], v[126:129]
	v_mfma_f32_16x16x32_bf16 v[122:125], v[138:141], v[162:165], 0
	v_mfma_f32_16x16x32_bf16 v[122:125], v[142:145], v[166:169], v[122:125]
	v_mfma_f32_16x16x32_bf16 v[110:113], v[130:133], v[170:173], 0
	v_mfma_f32_16x16x32_bf16 v[110:113], v[134:137], v[174:177], v[110:113]
	v_mfma_f32_16x16x32_bf16 v[106:109], v[138:141], v[170:173], 0
	v_mfma_f32_16x16x32_bf16 v[106:109], v[142:145], v[174:177], v[106:109]
	v_mfma_f32_16x16x32_bf16 v[94:97], v[130:133], v[196:199], 0
	v_mfma_f32_16x16x32_bf16 v[94:97], v[134:137], v[200:203], v[94:97]
	v_mfma_f32_16x16x32_bf16 v[90:93], v[138:141], v[196:199], 0
	v_mfma_f32_16x16x32_bf16 v[90:93], v[142:145], v[200:203], v[90:93]
	v_mfma_f32_16x16x32_bf16 v[78:81], v[130:133], v[214:217], 0
	v_mfma_f32_16x16x32_bf16 v[78:81], v[134:137], v[218:221], v[78:81]
	v_mfma_f32_16x16x32_bf16 v[74:77], v[138:141], v[214:217], 0
	v_mfma_f32_16x16x32_bf16 v[74:77], v[142:145], v[218:221], v[74:77]
	v_mfma_f32_16x16x32_bf16 v[118:121], v[146:149], v[162:165], 0
	v_mfma_f32_16x16x32_bf16 v[118:121], v[150:153], v[166:169], v[118:121]
	v_mfma_f32_16x16x32_bf16 v[114:117], v[154:157], v[162:165], 0
	v_mfma_f32_16x16x32_bf16 v[114:117], v[158:161], v[166:169], v[114:117]
	v_mfma_f32_16x16x32_bf16 v[102:105], v[146:149], v[170:173], 0
	v_mfma_f32_16x16x32_bf16 v[102:105], v[150:153], v[174:177], v[102:105]
	v_mfma_f32_16x16x32_bf16 v[98:101], v[154:157], v[170:173], 0
	v_mfma_f32_16x16x32_bf16 v[98:101], v[158:161], v[174:177], v[98:101]
	v_mfma_f32_16x16x32_bf16 v[86:89], v[146:149], v[196:199], 0
	v_mfma_f32_16x16x32_bf16 v[86:89], v[150:153], v[200:203], v[86:89]
	v_mfma_f32_16x16x32_bf16 v[82:85], v[154:157], v[196:199], 0
	v_mfma_f32_16x16x32_bf16 v[82:85], v[158:161], v[200:203], v[82:85]
	v_mfma_f32_16x16x32_bf16 v[70:73], v[146:149], v[214:217], 0
	v_mfma_f32_16x16x32_bf16 v[70:73], v[150:153], v[218:221], v[70:73]
	v_mfma_f32_16x16x32_bf16 v[66:69], v[154:157], v[214:217], 0
	v_mfma_f32_16x16x32_bf16 v[66:69], v[158:161], v[218:221], v[66:69]
	s_barrier
	s_add_i32 s73, s66, s46
	s_mov_b32 m0, s73
	ds_read_b128 v[162:165], v211 offset:16384
	ds_read_b128 v[166:169], v211 offset:17408
	ds_read_b128 v[170:173], v211 offset:18432
	ds_read_b128 v[174:177], v211 offset:19456
	ds_read_b128 v[196:199], v211 offset:20480
	ds_read_b128 v[200:203], v211 offset:21504
	ds_read_b128 v[214:217], v211 offset:22528
	ds_read_b128 v[218:221], v211 offset:23552
	global_load_lds_dwordx4 v180, s[40:41]
	s_add_i32 m0, s73, 0x2000
	s_add_u32 s74, s40, 0x100000
	s_addc_u32 s75, s41, 0
	s_add_i32 s73, s67, s46
	global_load_lds_dwordx4 v184, s[40:41]
	s_mov_b32 m0, s73
	s_nop 0
	global_load_lds_dwordx4 v180, s[74:75]
	s_add_i32 m0, s73, 0x2000
	s_nop 0
	global_load_lds_dwordx4 v184, s[74:75]
	s_mov_b32 m0, s47
	s_nop 0
	global_load_lds_dwordx4 v178, s[42:43]
	s_mov_b32 m0, s59
	s_nop 0
	global_load_lds_dwordx4 v182, s[42:43]
	s_waitcnt vmcnt(8)
	s_waitcnt lgkmcnt(0)
	s_barrier
	s_waitcnt lgkmcnt(0)
	v_mfma_f32_16x16x32_bf16 v[62:65], v[130:133], v[162:165], 0
	v_mfma_f32_16x16x32_bf16 v[62:65], v[134:137], v[166:169], v[62:65]
	v_mfma_f32_16x16x32_bf16 v[58:61], v[138:141], v[162:165], 0
	v_mfma_f32_16x16x32_bf16 v[58:61], v[142:145], v[166:169], v[58:61]
	v_mfma_f32_16x16x32_bf16 v[46:49], v[130:133], v[170:173], 0
	v_mfma_f32_16x16x32_bf16 v[46:49], v[134:137], v[174:177], v[46:49]
	v_mfma_f32_16x16x32_bf16 v[42:45], v[138:141], v[170:173], 0
	v_mfma_f32_16x16x32_bf16 v[42:45], v[142:145], v[174:177], v[42:45]
	v_mfma_f32_16x16x32_bf16 v[30:33], v[130:133], v[196:199], 0
	v_mfma_f32_16x16x32_bf16 v[30:33], v[134:137], v[200:203], v[30:33]
	v_mfma_f32_16x16x32_bf16 v[26:29], v[138:141], v[196:199], 0
	v_mfma_f32_16x16x32_bf16 v[26:29], v[142:145], v[200:203], v[26:29]
	v_mfma_f32_16x16x32_bf16 v[14:17], v[130:133], v[214:217], 0
	v_mfma_f32_16x16x32_bf16 v[14:17], v[134:137], v[218:221], v[14:17]
	v_mfma_f32_16x16x32_bf16 v[10:13], v[138:141], v[214:217], 0
	v_mfma_f32_16x16x32_bf16 v[10:13], v[142:145], v[218:221], v[10:13]
	v_mfma_f32_16x16x32_bf16 v[54:57], v[146:149], v[162:165], 0
	v_mfma_f32_16x16x32_bf16 v[54:57], v[150:153], v[166:169], v[54:57]
	v_mfma_f32_16x16x32_bf16 v[50:53], v[154:157], v[162:165], 0
	v_mfma_f32_16x16x32_bf16 v[50:53], v[158:161], v[166:169], v[50:53]
	v_mfma_f32_16x16x32_bf16 v[38:41], v[146:149], v[170:173], 0
	v_mfma_f32_16x16x32_bf16 v[38:41], v[150:153], v[174:177], v[38:41]
	v_mfma_f32_16x16x32_bf16 v[34:37], v[154:157], v[170:173], 0
	v_mfma_f32_16x16x32_bf16 v[34:37], v[158:161], v[174:177], v[34:37]
	v_mfma_f32_16x16x32_bf16 v[22:25], v[146:149], v[196:199], 0
	v_mfma_f32_16x16x32_bf16 v[22:25], v[150:153], v[200:203], v[22:25]
	v_mfma_f32_16x16x32_bf16 v[18:21], v[154:157], v[196:199], 0
	v_mfma_f32_16x16x32_bf16 v[18:21], v[158:161], v[200:203], v[18:21]
	v_mfma_f32_16x16x32_bf16 v[6:9], v[146:149], v[214:217], 0
	v_mfma_f32_16x16x32_bf16 v[6:9], v[150:153], v[218:221], v[6:9]
	v_mfma_f32_16x16x32_bf16 v[2:5], v[154:157], v[214:217], 0
	v_mfma_f32_16x16x32_bf16 v[2:5], v[158:161], v[218:221], v[2:5]
	s_barrier
	s_add_i32 s73, 0, 0x18000
	s_add_i32 s74, 0, 0x1c000
	v_add_u32_e32 v142, s73, v208
	v_add_u32_e32 v158, s74, v208
	ds_read_b128 v[130:133], v142
	ds_read_b128 v[134:137], v142 offset:1024
	ds_read_b128 v[138:141], v142 offset:2048
	ds_read_b128 v[142:145], v142 offset:3072
	ds_read_b128 v[146:149], v158
	ds_read_b128 v[150:153], v158 offset:1024
	ds_read_b128 v[154:157], v158 offset:2048
	ds_read_b128 v[158:161], v158 offset:3072
	s_add_u32 s42, s42, 0x100000
	s_addc_u32 s43, s43, 0
	s_mov_b32 m0, s60
	ds_read_b128 v[162:165], v211 offset:32768
	ds_read_b128 v[166:169], v211 offset:33792
	ds_read_b128 v[170:173], v211 offset:34816
	ds_read_b128 v[174:177], v211 offset:35840
	ds_read_b128 v[196:199], v211 offset:36864
	ds_read_b128 v[200:203], v211 offset:37888
	ds_read_b128 v[214:217], v211 offset:38912
	ds_read_b128 v[218:221], v211 offset:39936
	global_load_lds_dwordx4 v178, s[42:43]
	s_mov_b32 m0, s61
	s_nop 0
	global_load_lds_dwordx4 v182, s[42:43]
	s_waitcnt vmcnt(8)
	s_waitcnt lgkmcnt(0)
	s_barrier
	s_waitcnt lgkmcnt(0)
	v_mfma_f32_16x16x32_bf16 v[126:129], v[130:133], v[162:165], v[126:129]
	v_mfma_f32_16x16x32_bf16 v[126:129], v[134:137], v[166:169], v[126:129]
	v_mfma_f32_16x16x32_bf16 v[122:125], v[138:141], v[162:165], v[122:125]
	v_mfma_f32_16x16x32_bf16 v[122:125], v[142:145], v[166:169], v[122:125]
	v_mfma_f32_16x16x32_bf16 v[110:113], v[130:133], v[170:173], v[110:113]
	v_mfma_f32_16x16x32_bf16 v[110:113], v[134:137], v[174:177], v[110:113]
	v_mfma_f32_16x16x32_bf16 v[106:109], v[138:141], v[170:173], v[106:109]
	v_mfma_f32_16x16x32_bf16 v[106:109], v[142:145], v[174:177], v[106:109]
	v_mfma_f32_16x16x32_bf16 v[94:97], v[130:133], v[196:199], v[94:97]
	v_mfma_f32_16x16x32_bf16 v[94:97], v[134:137], v[200:203], v[94:97]
	v_mfma_f32_16x16x32_bf16 v[90:93], v[138:141], v[196:199], v[90:93]
	v_mfma_f32_16x16x32_bf16 v[90:93], v[142:145], v[200:203], v[90:93]
	v_mfma_f32_16x16x32_bf16 v[78:81], v[130:133], v[214:217], v[78:81]
	v_mfma_f32_16x16x32_bf16 v[78:81], v[134:137], v[218:221], v[78:81]
	v_mfma_f32_16x16x32_bf16 v[74:77], v[138:141], v[214:217], v[74:77]
	v_mfma_f32_16x16x32_bf16 v[74:77], v[142:145], v[218:221], v[74:77]
	v_mfma_f32_16x16x32_bf16 v[118:121], v[146:149], v[162:165], v[118:121]
	v_mfma_f32_16x16x32_bf16 v[118:121], v[150:153], v[166:169], v[118:121]
	v_mfma_f32_16x16x32_bf16 v[114:117], v[154:157], v[162:165], v[114:117]
	v_mfma_f32_16x16x32_bf16 v[114:117], v[158:161], v[166:169], v[114:117]
	v_mfma_f32_16x16x32_bf16 v[102:105], v[146:149], v[170:173], v[102:105]
	v_mfma_f32_16x16x32_bf16 v[102:105], v[150:153], v[174:177], v[102:105]
	v_mfma_f32_16x16x32_bf16 v[98:101], v[154:157], v[170:173], v[98:101]
	v_mfma_f32_16x16x32_bf16 v[98:101], v[158:161], v[174:177], v[98:101]
	v_mfma_f32_16x16x32_bf16 v[86:89], v[146:149], v[196:199], v[86:89]
	v_mfma_f32_16x16x32_bf16 v[86:89], v[150:153], v[200:203], v[86:89]
	v_mfma_f32_16x16x32_bf16 v[82:85], v[154:157], v[196:199], v[82:85]
	v_mfma_f32_16x16x32_bf16 v[82:85], v[158:161], v[200:203], v[82:85]
	v_mfma_f32_16x16x32_bf16 v[70:73], v[146:149], v[214:217], v[70:73]
	v_mfma_f32_16x16x32_bf16 v[70:73], v[150:153], v[218:221], v[70:73]
	v_mfma_f32_16x16x32_bf16 v[66:69], v[154:157], v[214:217], v[66:69]
	v_mfma_f32_16x16x32_bf16 v[66:69], v[158:161], v[218:221], v[66:69]
	s_barrier
	s_add_u32 s42, s40, 0x4000
	s_addc_u32 s43, s41, 0
	s_add_i32 s73, s73, s46
	s_mov_b32 m0, s73
	ds_read_b128 v[162:165], v211 offset:49152
	ds_read_b128 v[166:169], v211 offset:50176
	ds_read_b128 v[170:173], v211 offset:51200
	ds_read_b128 v[174:177], v211 offset:52224
	ds_read_b128 v[196:199], v211 offset:53248
	ds_read_b128 v[200:203], v211 offset:54272
	ds_read_b128 v[214:217], v211 offset:55296
	ds_read_b128 v[218:221], v211 offset:56320
	global_load_lds_dwordx4 v180, s[42:43]
	s_add_i32 m0, s73, 0x2000
	s_add_u32 s40, s40, 0x104000
	s_addc_u32 s41, s41, 0
	global_load_lds_dwordx4 v184, s[42:43]
	s_add_i32 s42, s74, s46
	s_mov_b32 m0, s42
	s_nop 0
	global_load_lds_dwordx4 v180, s[40:41]
	s_add_i32 m0, s42, 0x2000
	s_nop 0
	global_load_lds_dwordx4 v184, s[40:41]
	s_mov_b32 m0, s64
	s_nop 0
	global_load_lds_dwordx4 v178, s[38:39]
	s_mov_b32 m0, s65
	s_nop 0
	global_load_lds_dwordx4 v182, s[38:39]
	s_waitcnt vmcnt(8)
	s_waitcnt lgkmcnt(0)
	s_barrier
	s_waitcnt lgkmcnt(0)
	v_mfma_f32_16x16x32_bf16 v[62:65], v[130:133], v[162:165], v[62:65]
	v_mfma_f32_16x16x32_bf16 v[62:65], v[134:137], v[166:169], v[62:65]
	v_mfma_f32_16x16x32_bf16 v[58:61], v[138:141], v[162:165], v[58:61]
	v_mfma_f32_16x16x32_bf16 v[58:61], v[142:145], v[166:169], v[58:61]
	v_mfma_f32_16x16x32_bf16 v[46:49], v[130:133], v[170:173], v[46:49]
	v_mfma_f32_16x16x32_bf16 v[46:49], v[134:137], v[174:177], v[46:49]
	v_mfma_f32_16x16x32_bf16 v[42:45], v[138:141], v[170:173], v[42:45]
	v_mfma_f32_16x16x32_bf16 v[42:45], v[142:145], v[174:177], v[42:45]
	v_mfma_f32_16x16x32_bf16 v[30:33], v[130:133], v[196:199], v[30:33]
	v_mfma_f32_16x16x32_bf16 v[30:33], v[134:137], v[200:203], v[30:33]
	v_mfma_f32_16x16x32_bf16 v[26:29], v[138:141], v[196:199], v[26:29]
	v_mfma_f32_16x16x32_bf16 v[26:29], v[142:145], v[200:203], v[26:29]
	v_mfma_f32_16x16x32_bf16 v[14:17], v[130:133], v[214:217], v[14:17]
	v_mfma_f32_16x16x32_bf16 v[14:17], v[134:137], v[218:221], v[14:17]
	v_mfma_f32_16x16x32_bf16 v[10:13], v[138:141], v[214:217], v[10:13]
	v_mfma_f32_16x16x32_bf16 v[10:13], v[142:145], v[218:221], v[10:13]
	v_mfma_f32_16x16x32_bf16 v[54:57], v[146:149], v[162:165], v[54:57]
	v_mfma_f32_16x16x32_bf16 v[54:57], v[150:153], v[166:169], v[54:57]
	v_mfma_f32_16x16x32_bf16 v[50:53], v[154:157], v[162:165], v[50:53]
	v_mfma_f32_16x16x32_bf16 v[50:53], v[158:161], v[166:169], v[50:53]
	v_mfma_f32_16x16x32_bf16 v[38:41], v[146:149], v[170:173], v[38:41]
	v_mfma_f32_16x16x32_bf16 v[38:41], v[150:153], v[174:177], v[38:41]
	v_mfma_f32_16x16x32_bf16 v[34:37], v[154:157], v[170:173], v[34:37]
	v_mfma_f32_16x16x32_bf16 v[34:37], v[158:161], v[174:177], v[34:37]
	v_mfma_f32_16x16x32_bf16 v[22:25], v[146:149], v[196:199], v[22:25]
	v_mfma_f32_16x16x32_bf16 v[22:25], v[150:153], v[200:203], v[22:25]
	v_mfma_f32_16x16x32_bf16 v[18:21], v[154:157], v[196:199], v[18:21]
	v_mfma_f32_16x16x32_bf16 v[18:21], v[158:161], v[200:203], v[18:21]
	v_mfma_f32_16x16x32_bf16 v[6:9], v[146:149], v[214:217], v[6:9]
	v_mfma_f32_16x16x32_bf16 v[6:9], v[150:153], v[218:221], v[6:9]
	v_mfma_f32_16x16x32_bf16 v[2:5], v[154:157], v[214:217], v[2:5]
	v_mfma_f32_16x16x32_bf16 v[2:5], v[158:161], v[218:221], v[2:5]
	s_barrier
	s_add_i32 s72, s72, 2
	s_add_u32 s36, s36, 0x8000
	s_addc_u32 s37, s37, 0
	s_add_u32 s70, s70, 0x8000
	s_addc_u32 s71, s71, 0
	s_cmp_gt_u32 s72, 61

.LBB0_1214:
	s_ashr_i32 s21, s20, 31
	s_lshl_b64 s[22:23], s[20:21], 21
	s_add_u32 s22, s10, s22
	s_addc_u32 s23, s11, s23
	s_and_b64 s[24:25], s[4:5], exec
	s_cselect_b32 s21, s23, s29
	s_cselect_b32 s56, s22, s28
	s_ashr_i32 s19, s18, 31
	s_lshl_b64 s[24:25], s[18:19], 21
	s_add_u32 s24, s65, s24
	v_readlane_b32 s19, v251, 50
	s_addc_u32 s25, s19, s25
	s_and_b64 s[34:35], s[4:5], exec
	s_cselect_b32 s19, s25, s31
	s_cselect_b32 s57, s24, s30
	s_add_u32 s28, s28, 0x104000
	s_addc_u32 s29, s29, 0
	s_add_u32 s59, s30, 0x8000
	s_addc_u32 s60, s31, 0
	s_mov_b32 s61, -2
	ds_read_b128 v[160:163], v154
	ds_read_b128 v[164:167], v154 offset:1024
	ds_read_b128 v[168:171], v154 offset:2048
	ds_read_b128 v[172:175], v154 offset:3072
	ds_read_b128 v[176:179], v155
	ds_read_b128 v[180:183], v155 offset:1024
	ds_read_b128 v[184:187], v155 offset:2048
	ds_read_b128 v[188:191], v155 offset:3072
	s_add_u32 s30, s28, 0xfff04000
	s_addc_u32 s31, s29, -1
	s_cmp_eq_u32 s61, 60
	s_cselect_b32 s36, s56, s30
	s_cselect_b32 s37, s21, s31
	s_cselect_b32 s34, s57, s59
	s_cselect_b32 s35, s19, s60
	s_add_u32 s30, s36, 0x4000
	s_addc_u32 s31, s37, 0
	s_add_i32 m0, s39, 0xc000
	ds_read_b128 v[192:195], v156
	ds_read_b128 v[196:199], v156 offset:1024
	ds_read_b128 v[200:203], v156 offset:2048
	ds_read_b128 v[204:207], v156 offset:3072
	ds_read_b128 v[208:211], v156 offset:4096
	ds_read_b128 v[212:215], v156 offset:5120
	ds_read_b128 v[216:219], v156 offset:6144
	ds_read_b128 v[220:223], v156 offset:7168
	global_load_lds_dwordx4 v140, s[28:29]
	s_add_i32 m0, s39, 0xe000
	s_nop 0
	global_load_lds_dwordx4 v142, s[28:29]
	s_waitcnt vmcnt(8)
	s_waitcnt lgkmcnt(0)
	s_barrier
	s_waitcnt lgkmcnt(0)
	v_mfma_f32_16x16x32_bf16 v[126:129], v[160:163], v[192:195], 0
	v_mfma_f32_16x16x32_bf16 v[126:129], v[164:167], v[196:199], v[126:129]
	v_mfma_f32_16x16x32_bf16 v[122:125], v[168:171], v[192:195], 0
	v_mfma_f32_16x16x32_bf16 v[122:125], v[172:175], v[196:199], v[122:125]
	v_mfma_f32_16x16x32_bf16 v[110:113], v[160:163], v[200:203], 0
	v_mfma_f32_16x16x32_bf16 v[110:113], v[164:167], v[204:207], v[110:113]
	v_mfma_f32_16x16x32_bf16 v[106:109], v[168:171], v[200:203], 0
	v_mfma_f32_16x16x32_bf16 v[106:109], v[172:175], v[204:207], v[106:109]
	v_mfma_f32_16x16x32_bf16 v[94:97], v[160:163], v[208:211], 0
	v_mfma_f32_16x16x32_bf16 v[94:97], v[164:167], v[212:215], v[94:97]
	v_mfma_f32_16x16x32_bf16 v[90:93], v[168:171], v[208:211], 0
	v_mfma_f32_16x16x32_bf16 v[90:93], v[172:175], v[212:215], v[90:93]
	v_mfma_f32_16x16x32_bf16 v[78:81], v[160:163], v[216:219], 0
	v_mfma_f32_16x16x32_bf16 v[78:81], v[164:167], v[220:223], v[78:81]
	v_mfma_f32_16x16x32_bf16 v[74:77], v[168:171], v[216:219], 0
	v_mfma_f32_16x16x32_bf16 v[74:77], v[172:175], v[220:223], v[74:77]
	v_mfma_f32_16x16x32_bf16 v[118:121], v[176:179], v[192:195], 0
	v_mfma_f32_16x16x32_bf16 v[118:121], v[180:183], v[196:199], v[118:121]
	v_mfma_f32_16x16x32_bf16 v[114:117], v[184:187], v[192:195], 0
	v_mfma_f32_16x16x32_bf16 v[114:117], v[188:191], v[196:199], v[114:117]
	v_mfma_f32_16x16x32_bf16 v[102:105], v[176:179], v[200:203], 0
	v_mfma_f32_16x16x32_bf16 v[102:105], v[180:183], v[204:207], v[102:105]
	v_mfma_f32_16x16x32_bf16 v[98:101], v[184:187], v[200:203], 0
	v_mfma_f32_16x16x32_bf16 v[98:101], v[188:191], v[204:207], v[98:101]
	v_mfma_f32_16x16x32_bf16 v[86:89], v[176:179], v[208:211], 0
	v_mfma_f32_16x16x32_bf16 v[86:89], v[180:183], v[212:215], v[86:89]
	v_mfma_f32_16x16x32_bf16 v[82:85], v[184:187], v[208:211], 0
	v_mfma_f32_16x16x32_bf16 v[82:85], v[188:191], v[212:215], v[82:85]
	v_mfma_f32_16x16x32_bf16 v[70:73], v[176:179], v[216:219], 0
	v_mfma_f32_16x16x32_bf16 v[70:73], v[180:183], v[220:223], v[70:73]
	v_mfma_f32_16x16x32_bf16 v[66:69], v[184:187], v[216:219], 0
	v_mfma_f32_16x16x32_bf16 v[66:69], v[188:191], v[220:223], v[66:69]
	s_barrier
	s_add_i32 s62, s47, s38
	s_mov_b32 m0, s62
	ds_read_b128 v[192:195], v156 offset:16384
	ds_read_b128 v[196:199], v156 offset:17408
	ds_read_b128 v[200:203], v156 offset:18432
	ds_read_b128 v[204:207], v156 offset:19456
	ds_read_b128 v[208:211], v156 offset:20480
	ds_read_b128 v[212:215], v156 offset:21504
	ds_read_b128 v[216:219], v156 offset:22528
	ds_read_b128 v[220:223], v156 offset:23552
	global_load_lds_dwordx4 v134, s[34:35]
	s_add_i32 m0, s62, 0x2000
	s_add_u32 s62, s34, 0x100000
	s_addc_u32 s63, s35, 0
	s_add_i32 s64, s54, s38
	global_load_lds_dwordx4 v130, s[34:35]
	s_mov_b32 m0, s64
	s_nop 0
	global_load_lds_dwordx4 v134, s[62:63]
	s_add_i32 m0, s64, 0x2000
	s_nop 0
	global_load_lds_dwordx4 v130, s[62:63]
	s_mov_b32 m0, s39
	s_nop 0
	global_load_lds_dwordx4 v136, s[36:37]
	s_mov_b32 m0, s40
	s_nop 0
	global_load_lds_dwordx4 v132, s[36:37]
	s_waitcnt vmcnt(8)
	s_waitcnt lgkmcnt(0)
	s_barrier
	s_waitcnt lgkmcnt(0)
	v_mfma_f32_16x16x32_bf16 v[62:65], v[160:163], v[192:195], 0
	v_mfma_f32_16x16x32_bf16 v[62:65], v[164:167], v[196:199], v[62:65]
	v_mfma_f32_16x16x32_bf16 v[58:61], v[168:171], v[192:195], 0
	v_mfma_f32_16x16x32_bf16 v[58:61], v[172:175], v[196:199], v[58:61]
	v_mfma_f32_16x16x32_bf16 v[46:49], v[160:163], v[200:203], 0
	v_mfma_f32_16x16x32_bf16 v[46:49], v[164:167], v[204:207], v[46:49]
	v_mfma_f32_16x16x32_bf16 v[42:45], v[168:171], v[200:203], 0
	v_mfma_f32_16x16x32_bf16 v[42:45], v[172:175], v[204:207], v[42:45]
	v_mfma_f32_16x16x32_bf16 v[30:33], v[160:163], v[208:211], 0
	v_mfma_f32_16x16x32_bf16 v[30:33], v[164:167], v[212:215], v[30:33]
	v_mfma_f32_16x16x32_bf16 v[26:29], v[168:171], v[208:211], 0
	v_mfma_f32_16x16x32_bf16 v[26:29], v[172:175], v[212:215], v[26:29]
	v_mfma_f32_16x16x32_bf16 v[14:17], v[160:163], v[216:219], 0
	v_mfma_f32_16x16x32_bf16 v[14:17], v[164:167], v[220:223], v[14:17]
	v_mfma_f32_16x16x32_bf16 v[10:13], v[168:171], v[216:219], 0
	v_mfma_f32_16x16x32_bf16 v[10:13], v[172:175], v[220:223], v[10:13]
	v_mfma_f32_16x16x32_bf16 v[54:57], v[176:179], v[192:195], 0
	v_mfma_f32_16x16x32_bf16 v[54:57], v[180:183], v[196:199], v[54:57]
	v_mfma_f32_16x16x32_bf16 v[50:53], v[184:187], v[192:195], 0
	v_mfma_f32_16x16x32_bf16 v[50:53], v[188:191], v[196:199], v[50:53]
	v_mfma_f32_16x16x32_bf16 v[38:41], v[176:179], v[200:203], 0
	v_mfma_f32_16x16x32_bf16 v[38:41], v[180:183], v[204:207], v[38:41]
	v_mfma_f32_16x16x32_bf16 v[34:37], v[184:187], v[200:203], 0
	v_mfma_f32_16x16x32_bf16 v[34:37], v[188:191], v[204:207], v[34:37]
	v_mfma_f32_16x16x32_bf16 v[22:25], v[176:179], v[208:211], 0
	v_mfma_f32_16x16x32_bf16 v[22:25], v[180:183], v[212:215], v[22:25]
	v_mfma_f32_16x16x32_bf16 v[18:21], v[184:187], v[208:211], 0
	v_mfma_f32_16x16x32_bf16 v[18:21], v[188:191], v[212:215], v[18:21]
	v_mfma_f32_16x16x32_bf16 v[6:9], v[176:179], v[216:219], 0
	v_mfma_f32_16x16x32_bf16 v[6:9], v[180:183], v[220:223], v[6:9]
	v_mfma_f32_16x16x32_bf16 v[2:5], v[184:187], v[216:219], 0
	v_mfma_f32_16x16x32_bf16 v[2:5], v[188:191], v[220:223], v[2:5]
	s_barrier
	s_add_i32 s62, 0, 0x18000
	v_add_u32_e32 v138, s62, v153
	s_add_i32 s63, 0, 0x1c000
	ds_read_b128 v[160:163], v138
	ds_read_b128 v[164:167], v138 offset:1024
	ds_read_b128 v[168:171], v138 offset:2048
	ds_read_b128 v[172:175], v138 offset:3072
	v_add_u32_e32 v138, s63, v153
	ds_read_b128 v[176:179], v138
	ds_read_b128 v[180:183], v138 offset:1024
	ds_read_b128 v[184:187], v138 offset:2048
	ds_read_b128 v[188:191], v138 offset:3072
	s_add_u32 s36, s36, 0x100000
	s_addc_u32 s37, s37, 0
	s_mov_b32 m0, s41
	ds_read_b128 v[192:195], v156 offset:32768
	ds_read_b128 v[196:199], v156 offset:33792
	ds_read_b128 v[200:203], v156 offset:34816
	ds_read_b128 v[204:207], v156 offset:35840
	ds_read_b128 v[208:211], v156 offset:36864
	ds_read_b128 v[212:215], v156 offset:37888
	ds_read_b128 v[216:219], v156 offset:38912
	ds_read_b128 v[220:223], v156 offset:39936
	global_load_lds_dwordx4 v136, s[36:37]
	s_mov_b32 m0, s42
	s_nop 0
	global_load_lds_dwordx4 v132, s[36:37]
	s_waitcnt vmcnt(8)
	s_waitcnt lgkmcnt(0)
	s_barrier
	s_waitcnt lgkmcnt(0)
	v_mfma_f32_16x16x32_bf16 v[126:129], v[160:163], v[192:195], v[126:129]
	v_mfma_f32_16x16x32_bf16 v[126:129], v[164:167], v[196:199], v[126:129]
	v_mfma_f32_16x16x32_bf16 v[122:125], v[168:171], v[192:195], v[122:125]
	v_mfma_f32_16x16x32_bf16 v[122:125], v[172:175], v[196:199], v[122:125]
	v_mfma_f32_16x16x32_bf16 v[110:113], v[160:163], v[200:203], v[110:113]
	v_mfma_f32_16x16x32_bf16 v[110:113], v[164:167], v[204:207], v[110:113]
	v_mfma_f32_16x16x32_bf16 v[106:109], v[168:171], v[200:203], v[106:109]
	v_mfma_f32_16x16x32_bf16 v[106:109], v[172:175], v[204:207], v[106:109]
	v_mfma_f32_16x16x32_bf16 v[94:97], v[160:163], v[208:211], v[94:97]
	v_mfma_f32_16x16x32_bf16 v[94:97], v[164:167], v[212:215], v[94:97]
	v_mfma_f32_16x16x32_bf16 v[90:93], v[168:171], v[208:211], v[90:93]
	v_mfma_f32_16x16x32_bf16 v[90:93], v[172:175], v[212:215], v[90:93]
	v_mfma_f32_16x16x32_bf16 v[78:81], v[160:163], v[216:219], v[78:81]
	v_mfma_f32_16x16x32_bf16 v[78:81], v[164:167], v[220:223], v[78:81]
	v_mfma_f32_16x16x32_bf16 v[74:77], v[168:171], v[216:219], v[74:77]
	v_mfma_f32_16x16x32_bf16 v[74:77], v[172:175], v[220:223], v[74:77]
	v_mfma_f32_16x16x32_bf16 v[118:121], v[176:179], v[192:195], v[118:121]
	v_mfma_f32_16x16x32_bf16 v[118:121], v[180:183], v[196:199], v[118:121]
	v_mfma_f32_16x16x32_bf16 v[114:117], v[184:187], v[192:195], v[114:117]
	v_mfma_f32_16x16x32_bf16 v[114:117], v[188:191], v[196:199], v[114:117]
	v_mfma_f32_16x16x32_bf16 v[102:105], v[176:179], v[200:203], v[102:105]
	v_mfma_f32_16x16x32_bf16 v[102:105], v[180:183], v[204:207], v[102:105]
	v_mfma_f32_16x16x32_bf16 v[98:101], v[184:187], v[200:203], v[98:101]
	v_mfma_f32_16x16x32_bf16 v[98:101], v[188:191], v[204:207], v[98:101]
	v_mfma_f32_16x16x32_bf16 v[86:89], v[176:179], v[208:211], v[86:89]
	v_mfma_f32_16x16x32_bf16 v[86:89], v[180:183], v[212:215], v[86:89]
	v_mfma_f32_16x16x32_bf16 v[82:85], v[184:187], v[208:211], v[82:85]
	v_mfma_f32_16x16x32_bf16 v[82:85], v[188:191], v[212:215], v[82:85]
	v_mfma_f32_16x16x32_bf16 v[70:73], v[176:179], v[216:219], v[70:73]
	v_mfma_f32_16x16x32_bf16 v[70:73], v[180:183], v[220:223], v[70:73]
	v_mfma_f32_16x16x32_bf16 v[66:69], v[184:187], v[216:219], v[66:69]
	v_mfma_f32_16x16x32_bf16 v[66:69], v[188:191], v[220:223], v[66:69]
	s_barrier
	s_add_u32 s36, s34, 0x4000
	s_addc_u32 s37, s35, 0
	s_add_i32 s62, s62, s38
	s_mov_b32 m0, s62
	ds_read_b128 v[192:195], v156 offset:49152
	ds_read_b128 v[196:199], v156 offset:50176
	ds_read_b128 v[200:203], v156 offset:51200
	ds_read_b128 v[204:207], v156 offset:52224
	ds_read_b128 v[208:211], v156 offset:53248
	ds_read_b128 v[212:215], v156 offset:54272
	ds_read_b128 v[216:219], v156 offset:55296
	ds_read_b128 v[220:223], v156 offset:56320
	global_load_lds_dwordx4 v134, s[36:37]
	s_add_i32 m0, s62, 0x2000
	s_add_u32 s34, s34, 0x104000
	s_addc_u32 s35, s35, 0
	global_load_lds_dwordx4 v130, s[36:37]
	s_add_i32 s36, s63, s38
	s_mov_b32 m0, s36
	s_nop 0
	global_load_lds_dwordx4 v134, s[34:35]
	s_add_i32 m0, s36, 0x2000
	s_nop 0
	global_load_lds_dwordx4 v130, s[34:35]
	s_mov_b32 m0, s45
	s_nop 0
	global_load_lds_dwordx4 v136, s[30:31]
	s_mov_b32 m0, s46
	s_nop 0
	global_load_lds_dwordx4 v132, s[30:31]
	s_waitcnt vmcnt(8)
	s_waitcnt lgkmcnt(0)
	s_barrier
	s_waitcnt lgkmcnt(0)
	v_mfma_f32_16x16x32_bf16 v[62:65], v[160:163], v[192:195], v[62:65]
	v_mfma_f32_16x16x32_bf16 v[62:65], v[164:167], v[196:199], v[62:65]
	v_mfma_f32_16x16x32_bf16 v[58:61], v[168:171], v[192:195], v[58:61]
	v_mfma_f32_16x16x32_bf16 v[58:61], v[172:175], v[196:199], v[58:61]
	v_mfma_f32_16x16x32_bf16 v[46:49], v[160:163], v[200:203], v[46:49]
	v_mfma_f32_16x16x32_bf16 v[46:49], v[164:167], v[204:207], v[46:49]
	v_mfma_f32_16x16x32_bf16 v[42:45], v[168:171], v[200:203], v[42:45]
	v_mfma_f32_16x16x32_bf16 v[42:45], v[172:175], v[204:207], v[42:45]
	v_mfma_f32_16x16x32_bf16 v[30:33], v[160:163], v[208:211], v[30:33]
	v_mfma_f32_16x16x32_bf16 v[30:33], v[164:167], v[212:215], v[30:33]
	v_mfma_f32_16x16x32_bf16 v[26:29], v[168:171], v[208:211], v[26:29]
	v_mfma_f32_16x16x32_bf16 v[26:29], v[172:175], v[212:215], v[26:29]
	v_mfma_f32_16x16x32_bf16 v[14:17], v[160:163], v[216:219], v[14:17]
	v_mfma_f32_16x16x32_bf16 v[14:17], v[164:167], v[220:223], v[14:17]
	v_mfma_f32_16x16x32_bf16 v[10:13], v[168:171], v[216:219], v[10:13]
	v_mfma_f32_16x16x32_bf16 v[10:13], v[172:175], v[220:223], v[10:13]
	v_mfma_f32_16x16x32_bf16 v[54:57], v[176:179], v[192:195], v[54:57]
	v_mfma_f32_16x16x32_bf16 v[54:57], v[180:183], v[196:199], v[54:57]
	v_mfma_f32_16x16x32_bf16 v[50:53], v[184:187], v[192:195], v[50:53]
	v_mfma_f32_16x16x32_bf16 v[50:53], v[188:191], v[196:199], v[50:53]
	v_mfma_f32_16x16x32_bf16 v[38:41], v[176:179], v[200:203], v[38:41]
	v_mfma_f32_16x16x32_bf16 v[38:41], v[180:183], v[204:207], v[38:41]
	v_mfma_f32_16x16x32_bf16 v[34:37], v[184:187], v[200:203], v[34:37]
	v_mfma_f32_16x16x32_bf16 v[34:37], v[188:191], v[204:207], v[34:37]
	v_mfma_f32_16x16x32_bf16 v[22:25], v[176:179], v[208:211], v[22:25]
	v_mfma_f32_16x16x32_bf16 v[22:25], v[180:183], v[212:215], v[22:25]
	v_mfma_f32_16x16x32_bf16 v[18:21], v[184:187], v[208:211], v[18:21]
	v_mfma_f32_16x16x32_bf16 v[18:21], v[188:191], v[212:215], v[18:21]
	v_mfma_f32_16x16x32_bf16 v[6:9], v[176:179], v[216:219], v[6:9]
	v_mfma_f32_16x16x32_bf16 v[6:9], v[180:183], v[220:223], v[6:9]
	v_mfma_f32_16x16x32_bf16 v[2:5], v[184:187], v[216:219], v[2:5]
	v_mfma_f32_16x16x32_bf16 v[2:5], v[188:191], v[220:223], v[2:5]
	s_barrier
	s_add_i32 s61, s61, 2
	s_add_u32 s28, s28, 0x8000
	s_addc_u32 s29, s29, 0
	s_add_u32 s59, s59, 0x8000
	s_addc_u32 s60, s60, 0
	s_cmp_gt_u32 s61, 61

.LBB0_1291:
	s_ashr_i32 s29, s28, 31
	s_lshl_b64 s[30:31], s[28:29], 23
	s_add_u32 s30, s84, s30
	s_addc_u32 s31, s85, s31
	s_and_b64 s[34:35], s[6:7], exec
	s_cselect_b32 s14, s31, s41
	s_cselect_b32 s29, s30, s40
	s_ashr_i32 s27, s26, 31
	s_lshl_b64 s[34:35], s[26:27], 23
	s_add_u32 s34, s51, s34
	v_readlane_b32 s27, v251, 62
	s_addc_u32 s35, s27, s35
	s_and_b64 s[44:45], s[6:7], exec
	s_cselect_b32 s27, s35, s43
	s_cselect_b32 s37, s34, s42
	s_add_u32 s40, s40, 0x404000
	s_addc_u32 s41, s41, 0
	s_add_u32 s39, s42, 0x8000
	s_addc_u32 s65, s43, 0
	s_mov_b32 s66, -2
	s_waitcnt lgkmcnt(0)
	ds_read_b128 v[130:133], v206
	ds_read_b128 v[134:137], v206 offset:1024
	ds_read_b128 v[138:141], v206 offset:2048
	ds_read_b128 v[142:145], v206 offset:3072
	ds_read_b128 v[146:149], v207
	ds_read_b128 v[150:153], v207 offset:1024
	ds_read_b128 v[176:179], v207 offset:2048
	ds_read_b128 v[180:183], v207 offset:3072
	s_add_u32 s42, s40, 0xffc04000
	s_addc_u32 s43, s41, -1
	s_cmpk_eq_i32 s66, 0xfc
	s_cselect_b32 s46, s29, s42
	s_cselect_b32 s47, s14, s43
	s_cselect_b32 s44, s37, s39
	s_cselect_b32 s45, s27, s65
	s_add_u32 s42, s46, 0x4000
	s_addc_u32 s43, s47, 0
	s_add_i32 m0, s53, 0xc000
	ds_read_b128 v[184:187], v208
	ds_read_b128 v[188:191], v208 offset:1024
	ds_read_b128 v[192:195], v208 offset:2048
	ds_read_b128 v[196:199], v208 offset:3072
	ds_read_b128 v[210:213], v208 offset:4096
	ds_read_b128 v[214:217], v208 offset:5120
	ds_read_b128 v[218:221], v208 offset:6144
	ds_read_b128 v[222:225], v208 offset:7168
	global_load_lds_dwordx4 v166, s[40:41]
	s_add_i32 m0, s53, 0xe000
	s_nop 0
	global_load_lds_dwordx4 v168, s[40:41]
	s_waitcnt vmcnt(8)
	s_waitcnt lgkmcnt(0)
	s_barrier
	s_waitcnt lgkmcnt(0)
	v_mfma_f32_16x16x32_bf16 v[126:129], v[130:133], v[184:187], 0
	v_mfma_f32_16x16x32_bf16 v[126:129], v[134:137], v[188:191], v[126:129]
	v_mfma_f32_16x16x32_bf16 v[122:125], v[138:141], v[184:187], 0
	v_mfma_f32_16x16x32_bf16 v[122:125], v[142:145], v[188:191], v[122:125]
	v_mfma_f32_16x16x32_bf16 v[110:113], v[130:133], v[192:195], 0
	v_mfma_f32_16x16x32_bf16 v[110:113], v[134:137], v[196:199], v[110:113]
	v_mfma_f32_16x16x32_bf16 v[106:109], v[138:141], v[192:195], 0
	v_mfma_f32_16x16x32_bf16 v[106:109], v[142:145], v[196:199], v[106:109]
	v_mfma_f32_16x16x32_bf16 v[94:97], v[130:133], v[210:213], 0
	v_mfma_f32_16x16x32_bf16 v[94:97], v[134:137], v[214:217], v[94:97]
	v_mfma_f32_16x16x32_bf16 v[90:93], v[138:141], v[210:213], 0
	v_mfma_f32_16x16x32_bf16 v[90:93], v[142:145], v[214:217], v[90:93]
	v_mfma_f32_16x16x32_bf16 v[78:81], v[130:133], v[218:221], 0
	v_mfma_f32_16x16x32_bf16 v[78:81], v[134:137], v[222:225], v[78:81]
	v_mfma_f32_16x16x32_bf16 v[74:77], v[138:141], v[218:221], 0
	v_mfma_f32_16x16x32_bf16 v[74:77], v[142:145], v[222:225], v[74:77]
	v_mfma_f32_16x16x32_bf16 v[118:121], v[146:149], v[184:187], 0
	v_mfma_f32_16x16x32_bf16 v[118:121], v[150:153], v[188:191], v[118:121]
	v_mfma_f32_16x16x32_bf16 v[114:117], v[176:179], v[184:187], 0
	v_mfma_f32_16x16x32_bf16 v[114:117], v[180:183], v[188:191], v[114:117]
	v_mfma_f32_16x16x32_bf16 v[102:105], v[146:149], v[192:195], 0
	v_mfma_f32_16x16x32_bf16 v[102:105], v[150:153], v[196:199], v[102:105]
	v_mfma_f32_16x16x32_bf16 v[98:101], v[176:179], v[192:195], 0
	v_mfma_f32_16x16x32_bf16 v[98:101], v[180:183], v[196:199], v[98:101]
	v_mfma_f32_16x16x32_bf16 v[86:89], v[146:149], v[210:213], 0
	v_mfma_f32_16x16x32_bf16 v[86:89], v[150:153], v[214:217], v[86:89]
	v_mfma_f32_16x16x32_bf16 v[82:85], v[176:179], v[210:213], 0
	v_mfma_f32_16x16x32_bf16 v[82:85], v[180:183], v[214:217], v[82:85]
	v_mfma_f32_16x16x32_bf16 v[70:73], v[146:149], v[218:221], 0
	v_mfma_f32_16x16x32_bf16 v[70:73], v[150:153], v[222:225], v[70:73]
	v_mfma_f32_16x16x32_bf16 v[66:69], v[176:179], v[218:221], 0
	v_mfma_f32_16x16x32_bf16 v[66:69], v[180:183], v[222:225], v[66:69]
	s_barrier
	s_add_i32 s67, s62, s52
	s_mov_b32 m0, s67
	ds_read_b128 v[184:187], v208 offset:16384
	ds_read_b128 v[188:191], v208 offset:17408
	ds_read_b128 v[192:195], v208 offset:18432
	ds_read_b128 v[196:199], v208 offset:19456
	ds_read_b128 v[210:213], v208 offset:20480
	ds_read_b128 v[214:217], v208 offset:21504
	ds_read_b128 v[218:221], v208 offset:22528
	ds_read_b128 v[222:225], v208 offset:23552
	global_load_lds_dwordx4 v156, s[44:45]
	s_add_i32 m0, s67, 0x2000
	s_add_u32 s68, s44, 0x400000
	s_addc_u32 s69, s45, 0
	s_add_i32 s67, s63, s52
	global_load_lds_dwordx4 v160, s[44:45]
	s_mov_b32 m0, s67
	s_nop 0
	global_load_lds_dwordx4 v156, s[68:69]
	s_add_i32 m0, s67, 0x2000
	s_nop 0
	global_load_lds_dwordx4 v160, s[68:69]
	s_mov_b32 m0, s53
	s_nop 0
	global_load_lds_dwordx4 v154, s[46:47]
	s_mov_b32 m0, s54
	s_nop 0
	global_load_lds_dwordx4 v158, s[46:47]
	s_waitcnt vmcnt(8)
	s_waitcnt lgkmcnt(0)
	s_barrier
	s_waitcnt lgkmcnt(0)
	v_mfma_f32_16x16x32_bf16 v[62:65], v[130:133], v[184:187], 0
	v_mfma_f32_16x16x32_bf16 v[62:65], v[134:137], v[188:191], v[62:65]
	v_mfma_f32_16x16x32_bf16 v[58:61], v[138:141], v[184:187], 0
	v_mfma_f32_16x16x32_bf16 v[58:61], v[142:145], v[188:191], v[58:61]
	v_mfma_f32_16x16x32_bf16 v[46:49], v[130:133], v[192:195], 0
	v_mfma_f32_16x16x32_bf16 v[46:49], v[134:137], v[196:199], v[46:49]
	v_mfma_f32_16x16x32_bf16 v[42:45], v[138:141], v[192:195], 0
	v_mfma_f32_16x16x32_bf16 v[42:45], v[142:145], v[196:199], v[42:45]
	v_mfma_f32_16x16x32_bf16 v[30:33], v[130:133], v[210:213], 0
	v_mfma_f32_16x16x32_bf16 v[30:33], v[134:137], v[214:217], v[30:33]
	v_mfma_f32_16x16x32_bf16 v[26:29], v[138:141], v[210:213], 0
	v_mfma_f32_16x16x32_bf16 v[26:29], v[142:145], v[214:217], v[26:29]
	v_mfma_f32_16x16x32_bf16 v[14:17], v[130:133], v[218:221], 0
	v_mfma_f32_16x16x32_bf16 v[14:17], v[134:137], v[222:225], v[14:17]
	v_mfma_f32_16x16x32_bf16 v[10:13], v[138:141], v[218:221], 0
	v_mfma_f32_16x16x32_bf16 v[10:13], v[142:145], v[222:225], v[10:13]
	v_mfma_f32_16x16x32_bf16 v[54:57], v[146:149], v[184:187], 0
	v_mfma_f32_16x16x32_bf16 v[54:57], v[150:153], v[188:191], v[54:57]
	v_mfma_f32_16x16x32_bf16 v[50:53], v[176:179], v[184:187], 0
	v_mfma_f32_16x16x32_bf16 v[50:53], v[180:183], v[188:191], v[50:53]
	v_mfma_f32_16x16x32_bf16 v[38:41], v[146:149], v[192:195], 0
	v_mfma_f32_16x16x32_bf16 v[38:41], v[150:153], v[196:199], v[38:41]
	v_mfma_f32_16x16x32_bf16 v[34:37], v[176:179], v[192:195], 0
	v_mfma_f32_16x16x32_bf16 v[34:37], v[180:183], v[196:199], v[34:37]
	v_mfma_f32_16x16x32_bf16 v[22:25], v[146:149], v[210:213], 0
	v_mfma_f32_16x16x32_bf16 v[22:25], v[150:153], v[214:217], v[22:25]
	v_mfma_f32_16x16x32_bf16 v[18:21], v[176:179], v[210:213], 0
	v_mfma_f32_16x16x32_bf16 v[18:21], v[180:183], v[214:217], v[18:21]
	v_mfma_f32_16x16x32_bf16 v[6:9], v[146:149], v[218:221], 0
	v_mfma_f32_16x16x32_bf16 v[6:9], v[150:153], v[222:225], v[6:9]
	v_mfma_f32_16x16x32_bf16 v[2:5], v[176:179], v[218:221], 0
	v_mfma_f32_16x16x32_bf16 v[2:5], v[180:183], v[222:225], v[2:5]
	s_barrier
	s_add_i32 s67, 0, 0x18000
	s_add_i32 s68, 0, 0x1c000
	v_add_u32_e32 v142, s67, v203
	v_add_u32_e32 v162, s68, v203
	ds_read_b128 v[130:133], v142
	ds_read_b128 v[134:137], v142 offset:1024
	ds_read_b128 v[138:141], v142 offset:2048
	ds_read_b128 v[142:145], v142 offset:3072
	ds_read_b128 v[146:149], v162
	ds_read_b128 v[150:153], v162 offset:1024
	ds_read_b128 v[176:179], v162 offset:2048
	ds_read_b128 v[180:183], v162 offset:3072
	s_add_u32 s46, s46, 0x400000
	s_addc_u32 s47, s47, 0
	s_mov_b32 m0, s55
	ds_read_b128 v[184:187], v208 offset:32768
	ds_read_b128 v[188:191], v208 offset:33792
	ds_read_b128 v[192:195], v208 offset:34816
	ds_read_b128 v[196:199], v208 offset:35840
	ds_read_b128 v[210:213], v208 offset:36864
	ds_read_b128 v[214:217], v208 offset:37888
	ds_read_b128 v[218:221], v208 offset:38912
	ds_read_b128 v[222:225], v208 offset:39936
	global_load_lds_dwordx4 v154, s[46:47]
	s_mov_b32 m0, s56
	s_nop 0
	global_load_lds_dwordx4 v158, s[46:47]
	s_waitcnt vmcnt(8)
	s_waitcnt lgkmcnt(0)
	s_barrier
	s_waitcnt lgkmcnt(0)
	v_mfma_f32_16x16x32_bf16 v[126:129], v[130:133], v[184:187], v[126:129]
	v_mfma_f32_16x16x32_bf16 v[126:129], v[134:137], v[188:191], v[126:129]
	v_mfma_f32_16x16x32_bf16 v[122:125], v[138:141], v[184:187], v[122:125]
	v_mfma_f32_16x16x32_bf16 v[122:125], v[142:145], v[188:191], v[122:125]
	v_mfma_f32_16x16x32_bf16 v[110:113], v[130:133], v[192:195], v[110:113]
	v_mfma_f32_16x16x32_bf16 v[110:113], v[134:137], v[196:199], v[110:113]
	v_mfma_f32_16x16x32_bf16 v[106:109], v[138:141], v[192:195], v[106:109]
	v_mfma_f32_16x16x32_bf16 v[106:109], v[142:145], v[196:199], v[106:109]
	v_mfma_f32_16x16x32_bf16 v[94:97], v[130:133], v[210:213], v[94:97]
	v_mfma_f32_16x16x32_bf16 v[94:97], v[134:137], v[214:217], v[94:97]
	v_mfma_f32_16x16x32_bf16 v[90:93], v[138:141], v[210:213], v[90:93]
	v_mfma_f32_16x16x32_bf16 v[90:93], v[142:145], v[214:217], v[90:93]
	v_mfma_f32_16x16x32_bf16 v[78:81], v[130:133], v[218:221], v[78:81]
	v_mfma_f32_16x16x32_bf16 v[78:81], v[134:137], v[222:225], v[78:81]
	v_mfma_f32_16x16x32_bf16 v[74:77], v[138:141], v[218:221], v[74:77]
	v_mfma_f32_16x16x32_bf16 v[74:77], v[142:145], v[222:225], v[74:77]
	v_mfma_f32_16x16x32_bf16 v[118:121], v[146:149], v[184:187], v[118:121]
	v_mfma_f32_16x16x32_bf16 v[118:121], v[150:153], v[188:191], v[118:121]
	v_mfma_f32_16x16x32_bf16 v[114:117], v[176:179], v[184:187], v[114:117]
	v_mfma_f32_16x16x32_bf16 v[114:117], v[180:183], v[188:191], v[114:117]
	v_mfma_f32_16x16x32_bf16 v[102:105], v[146:149], v[192:195], v[102:105]
	v_mfma_f32_16x16x32_bf16 v[102:105], v[150:153], v[196:199], v[102:105]
	v_mfma_f32_16x16x32_bf16 v[98:101], v[176:179], v[192:195], v[98:101]
	v_mfma_f32_16x16x32_bf16 v[98:101], v[180:183], v[196:199], v[98:101]
	v_mfma_f32_16x16x32_bf16 v[86:89], v[146:149], v[210:213], v[86:89]
	v_mfma_f32_16x16x32_bf16 v[86:89], v[150:153], v[214:217], v[86:89]
	v_mfma_f32_16x16x32_bf16 v[82:85], v[176:179], v[210:213], v[82:85]
	v_mfma_f32_16x16x32_bf16 v[82:85], v[180:183], v[214:217], v[82:85]
	v_mfma_f32_16x16x32_bf16 v[70:73], v[146:149], v[218:221], v[70:73]
	v_mfma_f32_16x16x32_bf16 v[70:73], v[150:153], v[222:225], v[70:73]
	v_mfma_f32_16x16x32_bf16 v[66:69], v[176:179], v[218:221], v[66:69]
	v_mfma_f32_16x16x32_bf16 v[66:69], v[180:183], v[222:225], v[66:69]
	s_barrier
	s_add_u32 s46, s44, 0x4000
	s_addc_u32 s47, s45, 0
	s_add_i32 s67, s67, s52
	s_mov_b32 m0, s67
	ds_read_b128 v[184:187], v208 offset:49152
	ds_read_b128 v[188:191], v208 offset:50176
	ds_read_b128 v[192:195], v208 offset:51200
	ds_read_b128 v[196:199], v208 offset:52224
	ds_read_b128 v[210:213], v208 offset:53248
	ds_read_b128 v[214:217], v208 offset:54272
	ds_read_b128 v[218:221], v208 offset:55296
	ds_read_b128 v[222:225], v208 offset:56320
	global_load_lds_dwordx4 v156, s[46:47]
	s_add_i32 m0, s67, 0x2000
	s_add_u32 s44, s44, 0x404000
	s_addc_u32 s45, s45, 0
	global_load_lds_dwordx4 v160, s[46:47]
	s_add_i32 s46, s68, s52
	s_mov_b32 m0, s46
	s_nop 0
	global_load_lds_dwordx4 v156, s[44:45]
	s_add_i32 m0, s46, 0x2000
	s_nop 0
	global_load_lds_dwordx4 v160, s[44:45]
	s_mov_b32 m0, s60
	s_nop 0
	global_load_lds_dwordx4 v154, s[42:43]
	s_mov_b32 m0, s61
	s_nop 0
	global_load_lds_dwordx4 v158, s[42:43]
	s_waitcnt vmcnt(8)
	s_waitcnt lgkmcnt(0)
	s_barrier
	s_waitcnt lgkmcnt(0)
	v_mfma_f32_16x16x32_bf16 v[62:65], v[130:133], v[184:187], v[62:65]
	v_mfma_f32_16x16x32_bf16 v[62:65], v[134:137], v[188:191], v[62:65]
	v_mfma_f32_16x16x32_bf16 v[58:61], v[138:141], v[184:187], v[58:61]
	v_mfma_f32_16x16x32_bf16 v[58:61], v[142:145], v[188:191], v[58:61]
	v_mfma_f32_16x16x32_bf16 v[46:49], v[130:133], v[192:195], v[46:49]
	v_mfma_f32_16x16x32_bf16 v[46:49], v[134:137], v[196:199], v[46:49]
	v_mfma_f32_16x16x32_bf16 v[42:45], v[138:141], v[192:195], v[42:45]
	v_mfma_f32_16x16x32_bf16 v[42:45], v[142:145], v[196:199], v[42:45]
	v_mfma_f32_16x16x32_bf16 v[30:33], v[130:133], v[210:213], v[30:33]
	v_mfma_f32_16x16x32_bf16 v[30:33], v[134:137], v[214:217], v[30:33]
	v_mfma_f32_16x16x32_bf16 v[26:29], v[138:141], v[210:213], v[26:29]
	v_mfma_f32_16x16x32_bf16 v[26:29], v[142:145], v[214:217], v[26:29]
	v_mfma_f32_16x16x32_bf16 v[14:17], v[130:133], v[218:221], v[14:17]
	v_mfma_f32_16x16x32_bf16 v[14:17], v[134:137], v[222:225], v[14:17]
	v_mfma_f32_16x16x32_bf16 v[10:13], v[138:141], v[218:221], v[10:13]
	v_mfma_f32_16x16x32_bf16 v[10:13], v[142:145], v[222:225], v[10:13]
	v_mfma_f32_16x16x32_bf16 v[54:57], v[146:149], v[184:187], v[54:57]
	v_mfma_f32_16x16x32_bf16 v[54:57], v[150:153], v[188:191], v[54:57]
	v_mfma_f32_16x16x32_bf16 v[50:53], v[176:179], v[184:187], v[50:53]
	v_mfma_f32_16x16x32_bf16 v[50:53], v[180:183], v[188:191], v[50:53]
	v_mfma_f32_16x16x32_bf16 v[38:41], v[146:149], v[192:195], v[38:41]
	v_mfma_f32_16x16x32_bf16 v[38:41], v[150:153], v[196:199], v[38:41]
	v_mfma_f32_16x16x32_bf16 v[34:37], v[176:179], v[192:195], v[34:37]
	v_mfma_f32_16x16x32_bf16 v[34:37], v[180:183], v[196:199], v[34:37]
	v_mfma_f32_16x16x32_bf16 v[22:25], v[146:149], v[210:213], v[22:25]
	v_mfma_f32_16x16x32_bf16 v[22:25], v[150:153], v[214:217], v[22:25]
	v_mfma_f32_16x16x32_bf16 v[18:21], v[176:179], v[210:213], v[18:21]
	v_mfma_f32_16x16x32_bf16 v[18:21], v[180:183], v[214:217], v[18:21]
	v_mfma_f32_16x16x32_bf16 v[6:9], v[146:149], v[218:221], v[6:9]
	v_mfma_f32_16x16x32_bf16 v[6:9], v[150:153], v[222:225], v[6:9]
	v_mfma_f32_16x16x32_bf16 v[2:5], v[176:179], v[218:221], v[2:5]
	v_mfma_f32_16x16x32_bf16 v[2:5], v[180:183], v[222:225], v[2:5]
	s_barrier
	s_add_i32 s66, s66, 2
	s_add_u32 s40, s40, 0x8000
	s_addc_u32 s41, s41, 0
	s_add_u32 s39, s39, 0x8000
	s_addc_u32 s65, s65, 0
	s_cmpk_gt_u32 s66, 0xfd

.LBB0_1386:
	s_ashr_i32 s21, s20, 31
	s_lshl_b64 s[22:23], s[20:21], 21
	s_add_u32 s22, s0, s22
	s_addc_u32 s23, s1, s23
	s_and_b64 s[24:25], s[2:3], exec
	s_cselect_b32 s21, s23, s31
	s_cselect_b32 s27, s22, s30
	s_ashr_i32 s19, s18, 31
	s_lshl_b64 s[24:25], s[18:19], 21
	s_add_u32 s24, s48, s24
	s_addc_u32 s25, s49, s25
	s_and_b64 s[36:37], s[2:3], exec
	s_cselect_b32 s19, s25, s35
	s_cselect_b32 s29, s24, s34
	s_add_u32 s30, s30, 0x104000
	s_addc_u32 s31, s31, 0
	s_add_u32 s52, s34, 0x8000
	s_addc_u32 s53, s35, 0
	s_mov_b32 s54, -2
	ds_read_b128 v[62:65], v189
	ds_read_b128 v[66:69], v189 offset:1024
	ds_read_b128 v[74:77], v189 offset:2048
	ds_read_b128 v[78:81], v189 offset:3072
	ds_read_b128 v[146:149], v195
	ds_read_b128 v[150:153], v195 offset:1024
	ds_read_b128 v[154:157], v195 offset:2048
	ds_read_b128 v[158:161], v195 offset:3072
	s_add_u32 s34, s30, 0xfff04000
	s_addc_u32 s35, s31, -1
	s_cmp_eq_u32 s54, 60
	s_cselect_b32 s38, s27, s34
	s_cselect_b32 s39, s21, s35
	s_cselect_b32 s36, s29, s52
	s_cselect_b32 s37, s19, s53
	s_add_u32 s34, s38, 0x4000
	s_addc_u32 s35, s39, 0
	s_add_i32 m0, s40, 0xc000
	ds_read_b128 v[190:193], v197
	ds_read_b128 v[198:201], v197 offset:1024
	ds_read_b128 v[202:205], v197 offset:2048
	ds_read_b128 v[206:209], v197 offset:3072
	ds_read_b128 v[210:213], v197 offset:4096
	ds_read_b128 v[214:217], v197 offset:5120
	ds_read_b128 v[218:221], v197 offset:6144
	ds_read_b128 v[222:225], v197 offset:7168
	global_load_lds_dwordx4 v172, s[30:31]
	s_add_i32 m0, s40, 0xe000
	s_nop 0
	global_load_lds_dwordx4 v174, s[30:31]
	s_waitcnt vmcnt(8)
	s_waitcnt lgkmcnt(0)
	s_barrier
	s_waitcnt lgkmcnt(0)
	v_mfma_f32_16x16x32_bf16 v[142:145], v[62:65], v[190:193], 0
	v_mfma_f32_16x16x32_bf16 v[142:145], v[66:69], v[198:201], v[142:145]
	v_mfma_f32_16x16x32_bf16 v[138:141], v[74:77], v[190:193], 0
	v_mfma_f32_16x16x32_bf16 v[138:141], v[78:81], v[198:201], v[138:141]
	v_mfma_f32_16x16x32_bf16 v[126:129], v[62:65], v[202:205], 0
	v_mfma_f32_16x16x32_bf16 v[126:129], v[66:69], v[206:209], v[126:129]
	v_mfma_f32_16x16x32_bf16 v[122:125], v[74:77], v[202:205], 0
	v_mfma_f32_16x16x32_bf16 v[122:125], v[78:81], v[206:209], v[122:125]
	v_mfma_f32_16x16x32_bf16 v[110:113], v[62:65], v[210:213], 0
	v_mfma_f32_16x16x32_bf16 v[110:113], v[66:69], v[214:217], v[110:113]
	v_mfma_f32_16x16x32_bf16 v[106:109], v[74:77], v[210:213], 0
	v_mfma_f32_16x16x32_bf16 v[106:109], v[78:81], v[214:217], v[106:109]
	v_mfma_f32_16x16x32_bf16 v[94:97], v[62:65], v[218:221], 0
	v_mfma_f32_16x16x32_bf16 v[94:97], v[66:69], v[222:225], v[94:97]
	v_mfma_f32_16x16x32_bf16 v[90:93], v[74:77], v[218:221], 0
	v_mfma_f32_16x16x32_bf16 v[90:93], v[78:81], v[222:225], v[90:93]
	v_mfma_f32_16x16x32_bf16 v[134:137], v[146:149], v[190:193], 0
	v_mfma_f32_16x16x32_bf16 v[134:137], v[150:153], v[198:201], v[134:137]
	v_mfma_f32_16x16x32_bf16 v[130:133], v[154:157], v[190:193], 0
	v_mfma_f32_16x16x32_bf16 v[130:133], v[158:161], v[198:201], v[130:133]
	v_mfma_f32_16x16x32_bf16 v[118:121], v[146:149], v[202:205], 0
	v_mfma_f32_16x16x32_bf16 v[118:121], v[150:153], v[206:209], v[118:121]
	v_mfma_f32_16x16x32_bf16 v[114:117], v[154:157], v[202:205], 0
	v_mfma_f32_16x16x32_bf16 v[114:117], v[158:161], v[206:209], v[114:117]
	v_mfma_f32_16x16x32_bf16 v[102:105], v[146:149], v[210:213], 0
	v_mfma_f32_16x16x32_bf16 v[102:105], v[150:153], v[214:217], v[102:105]
	v_mfma_f32_16x16x32_bf16 v[98:101], v[154:157], v[210:213], 0
	v_mfma_f32_16x16x32_bf16 v[98:101], v[158:161], v[214:217], v[98:101]
	v_mfma_f32_16x16x32_bf16 v[86:89], v[146:149], v[218:221], 0
	v_mfma_f32_16x16x32_bf16 v[86:89], v[150:153], v[222:225], v[86:89]
	v_mfma_f32_16x16x32_bf16 v[82:85], v[154:157], v[218:221], 0
	v_mfma_f32_16x16x32_bf16 v[82:85], v[158:161], v[222:225], v[82:85]
	s_barrier
	s_add_i32 s55, s50, s33
	s_mov_b32 m0, s55
	ds_read_b128 v[190:193], v197 offset:16384
	ds_read_b128 v[198:201], v197 offset:17408
	ds_read_b128 v[202:205], v197 offset:18432
	ds_read_b128 v[206:209], v197 offset:19456
	ds_read_b128 v[210:213], v197 offset:20480
	ds_read_b128 v[214:217], v197 offset:21504
	ds_read_b128 v[218:221], v197 offset:22528
	ds_read_b128 v[222:225], v197 offset:23552
	global_load_lds_dwordx4 v166, s[36:37]
	s_add_i32 m0, s55, 0x2000
	s_add_u32 s56, s36, 0x100000
	s_addc_u32 s57, s37, 0
	s_add_i32 s55, s51, s33
	global_load_lds_dwordx4 v162, s[36:37]
	s_mov_b32 m0, s55
	s_nop 0
	global_load_lds_dwordx4 v166, s[56:57]
	s_add_i32 m0, s55, 0x2000
	s_nop 0
	global_load_lds_dwordx4 v162, s[56:57]
	s_mov_b32 m0, s40
	s_nop 0
	global_load_lds_dwordx4 v168, s[38:39]
	s_mov_b32 m0, s41
	s_nop 0
	global_load_lds_dwordx4 v164, s[38:39]
	s_waitcnt vmcnt(8)
	s_waitcnt lgkmcnt(0)
	s_barrier
	s_waitcnt lgkmcnt(0)
	v_mfma_f32_16x16x32_bf16 v[70:73], v[62:65], v[190:193], 0
	v_mfma_f32_16x16x32_bf16 v[70:73], v[66:69], v[198:201], v[70:73]
	v_mfma_f32_16x16x32_bf16 v[58:61], v[74:77], v[190:193], 0
	v_mfma_f32_16x16x32_bf16 v[58:61], v[78:81], v[198:201], v[58:61]
	v_mfma_f32_16x16x32_bf16 v[46:49], v[62:65], v[202:205], 0
	v_mfma_f32_16x16x32_bf16 v[46:49], v[66:69], v[206:209], v[46:49]
	v_mfma_f32_16x16x32_bf16 v[42:45], v[74:77], v[202:205], 0
	v_mfma_f32_16x16x32_bf16 v[42:45], v[78:81], v[206:209], v[42:45]
	v_mfma_f32_16x16x32_bf16 v[30:33], v[62:65], v[210:213], 0
	v_mfma_f32_16x16x32_bf16 v[30:33], v[66:69], v[214:217], v[30:33]
	v_mfma_f32_16x16x32_bf16 v[26:29], v[74:77], v[210:213], 0
	v_mfma_f32_16x16x32_bf16 v[26:29], v[78:81], v[214:217], v[26:29]
	v_mfma_f32_16x16x32_bf16 v[14:17], v[62:65], v[218:221], 0
	v_mfma_f32_16x16x32_bf16 v[14:17], v[66:69], v[222:225], v[14:17]
	v_mfma_f32_16x16x32_bf16 v[10:13], v[74:77], v[218:221], 0
	v_mfma_f32_16x16x32_bf16 v[10:13], v[78:81], v[222:225], v[10:13]
	v_mfma_f32_16x16x32_bf16 v[54:57], v[146:149], v[190:193], 0
	v_mfma_f32_16x16x32_bf16 v[54:57], v[150:153], v[198:201], v[54:57]
	v_mfma_f32_16x16x32_bf16 v[50:53], v[154:157], v[190:193], 0
	v_mfma_f32_16x16x32_bf16 v[50:53], v[158:161], v[198:201], v[50:53]
	v_mfma_f32_16x16x32_bf16 v[38:41], v[146:149], v[202:205], 0
	v_mfma_f32_16x16x32_bf16 v[38:41], v[150:153], v[206:209], v[38:41]
	v_mfma_f32_16x16x32_bf16 v[34:37], v[154:157], v[202:205], 0
	v_mfma_f32_16x16x32_bf16 v[34:37], v[158:161], v[206:209], v[34:37]
	v_mfma_f32_16x16x32_bf16 v[22:25], v[146:149], v[210:213], 0
	v_mfma_f32_16x16x32_bf16 v[22:25], v[150:153], v[214:217], v[22:25]
	v_mfma_f32_16x16x32_bf16 v[18:21], v[154:157], v[210:213], 0
	v_mfma_f32_16x16x32_bf16 v[18:21], v[158:161], v[214:217], v[18:21]
	v_mfma_f32_16x16x32_bf16 v[6:9], v[146:149], v[218:221], 0
	v_mfma_f32_16x16x32_bf16 v[6:9], v[150:153], v[222:225], v[6:9]
	v_mfma_f32_16x16x32_bf16 v[2:5], v[154:157], v[218:221], 0
	v_mfma_f32_16x16x32_bf16 v[2:5], v[158:161], v[222:225], v[2:5]
	s_barrier
	s_add_i32 s55, 0, 0x18000
	s_add_i32 s56, 0, 0x1c000
	v_add_u32_e32 v78, s55, v187
	v_add_u32_e32 v158, s56, v187
	ds_read_b128 v[62:65], v78
	ds_read_b128 v[66:69], v78 offset:1024
	ds_read_b128 v[74:77], v78 offset:2048
	ds_read_b128 v[78:81], v78 offset:3072
	ds_read_b128 v[146:149], v158
	ds_read_b128 v[150:153], v158 offset:1024
	ds_read_b128 v[154:157], v158 offset:2048
	ds_read_b128 v[158:161], v158 offset:3072
	s_add_u32 s38, s38, 0x100000
	s_addc_u32 s39, s39, 0
	s_mov_b32 m0, s42
	ds_read_b128 v[190:193], v197 offset:32768
	ds_read_b128 v[198:201], v197 offset:33792
	ds_read_b128 v[202:205], v197 offset:34816
	ds_read_b128 v[206:209], v197 offset:35840
	ds_read_b128 v[210:213], v197 offset:36864
	ds_read_b128 v[214:217], v197 offset:37888
	ds_read_b128 v[218:221], v197 offset:38912
	ds_read_b128 v[222:225], v197 offset:39936
	global_load_lds_dwordx4 v168, s[38:39]
	s_mov_b32 m0, s43
	s_nop 0
	global_load_lds_dwordx4 v164, s[38:39]
	s_waitcnt vmcnt(8)
	s_waitcnt lgkmcnt(0)
	s_barrier
	s_waitcnt lgkmcnt(0)
	v_mfma_f32_16x16x32_bf16 v[142:145], v[62:65], v[190:193], v[142:145]
	v_mfma_f32_16x16x32_bf16 v[142:145], v[66:69], v[198:201], v[142:145]
	v_mfma_f32_16x16x32_bf16 v[138:141], v[74:77], v[190:193], v[138:141]
	v_mfma_f32_16x16x32_bf16 v[138:141], v[78:81], v[198:201], v[138:141]
	v_mfma_f32_16x16x32_bf16 v[126:129], v[62:65], v[202:205], v[126:129]
	v_mfma_f32_16x16x32_bf16 v[126:129], v[66:69], v[206:209], v[126:129]
	v_mfma_f32_16x16x32_bf16 v[122:125], v[74:77], v[202:205], v[122:125]
	v_mfma_f32_16x16x32_bf16 v[122:125], v[78:81], v[206:209], v[122:125]
	v_mfma_f32_16x16x32_bf16 v[110:113], v[62:65], v[210:213], v[110:113]
	v_mfma_f32_16x16x32_bf16 v[110:113], v[66:69], v[214:217], v[110:113]
	v_mfma_f32_16x16x32_bf16 v[106:109], v[74:77], v[210:213], v[106:109]
	v_mfma_f32_16x16x32_bf16 v[106:109], v[78:81], v[214:217], v[106:109]
	v_mfma_f32_16x16x32_bf16 v[94:97], v[62:65], v[218:221], v[94:97]
	v_mfma_f32_16x16x32_bf16 v[94:97], v[66:69], v[222:225], v[94:97]
	v_mfma_f32_16x16x32_bf16 v[90:93], v[74:77], v[218:221], v[90:93]
	v_mfma_f32_16x16x32_bf16 v[90:93], v[78:81], v[222:225], v[90:93]
	v_mfma_f32_16x16x32_bf16 v[134:137], v[146:149], v[190:193], v[134:137]
	v_mfma_f32_16x16x32_bf16 v[134:137], v[150:153], v[198:201], v[134:137]
	v_mfma_f32_16x16x32_bf16 v[130:133], v[154:157], v[190:193], v[130:133]
	v_mfma_f32_16x16x32_bf16 v[130:133], v[158:161], v[198:201], v[130:133]
	v_mfma_f32_16x16x32_bf16 v[118:121], v[146:149], v[202:205], v[118:121]
	v_mfma_f32_16x16x32_bf16 v[118:121], v[150:153], v[206:209], v[118:121]
	v_mfma_f32_16x16x32_bf16 v[114:117], v[154:157], v[202:205], v[114:117]
	v_mfma_f32_16x16x32_bf16 v[114:117], v[158:161], v[206:209], v[114:117]
	v_mfma_f32_16x16x32_bf16 v[102:105], v[146:149], v[210:213], v[102:105]
	v_mfma_f32_16x16x32_bf16 v[102:105], v[150:153], v[214:217], v[102:105]
	v_mfma_f32_16x16x32_bf16 v[98:101], v[154:157], v[210:213], v[98:101]
	v_mfma_f32_16x16x32_bf16 v[98:101], v[158:161], v[214:217], v[98:101]
	v_mfma_f32_16x16x32_bf16 v[86:89], v[146:149], v[218:221], v[86:89]
	v_mfma_f32_16x16x32_bf16 v[86:89], v[150:153], v[222:225], v[86:89]
	v_mfma_f32_16x16x32_bf16 v[82:85], v[154:157], v[218:221], v[82:85]
	v_mfma_f32_16x16x32_bf16 v[82:85], v[158:161], v[222:225], v[82:85]
	s_barrier
	s_add_u32 s38, s36, 0x4000
	s_addc_u32 s39, s37, 0
	s_add_i32 s55, s55, s33
	s_mov_b32 m0, s55
	ds_read_b128 v[190:193], v197 offset:49152
	ds_read_b128 v[198:201], v197 offset:50176
	ds_read_b128 v[202:205], v197 offset:51200
	ds_read_b128 v[206:209], v197 offset:52224
	ds_read_b128 v[210:213], v197 offset:53248
	ds_read_b128 v[214:217], v197 offset:54272
	ds_read_b128 v[218:221], v197 offset:55296
	ds_read_b128 v[222:225], v197 offset:56320
	global_load_lds_dwordx4 v166, s[38:39]
	s_add_i32 m0, s55, 0x2000
	s_add_u32 s36, s36, 0x104000
	s_addc_u32 s37, s37, 0
	global_load_lds_dwordx4 v162, s[38:39]
	s_add_i32 s38, s56, s33
	s_mov_b32 m0, s38
	s_nop 0
	global_load_lds_dwordx4 v166, s[36:37]
	s_add_i32 m0, s38, 0x2000
	s_nop 0
	global_load_lds_dwordx4 v162, s[36:37]
	s_mov_b32 m0, s46
	s_nop 0
	global_load_lds_dwordx4 v168, s[34:35]
	s_mov_b32 m0, s47
	s_nop 0
	global_load_lds_dwordx4 v164, s[34:35]
	s_waitcnt vmcnt(8)
	s_waitcnt lgkmcnt(0)
	s_barrier
	s_waitcnt lgkmcnt(0)
	v_mfma_f32_16x16x32_bf16 v[70:73], v[62:65], v[190:193], v[70:73]
	v_mfma_f32_16x16x32_bf16 v[70:73], v[66:69], v[198:201], v[70:73]
	v_mfma_f32_16x16x32_bf16 v[58:61], v[74:77], v[190:193], v[58:61]
	v_mfma_f32_16x16x32_bf16 v[58:61], v[78:81], v[198:201], v[58:61]
	v_mfma_f32_16x16x32_bf16 v[46:49], v[62:65], v[202:205], v[46:49]
	v_mfma_f32_16x16x32_bf16 v[46:49], v[66:69], v[206:209], v[46:49]
	v_mfma_f32_16x16x32_bf16 v[42:45], v[74:77], v[202:205], v[42:45]
	v_mfma_f32_16x16x32_bf16 v[42:45], v[78:81], v[206:209], v[42:45]
	v_mfma_f32_16x16x32_bf16 v[30:33], v[62:65], v[210:213], v[30:33]
	v_mfma_f32_16x16x32_bf16 v[30:33], v[66:69], v[214:217], v[30:33]
	v_mfma_f32_16x16x32_bf16 v[26:29], v[74:77], v[210:213], v[26:29]
	v_mfma_f32_16x16x32_bf16 v[26:29], v[78:81], v[214:217], v[26:29]
	v_mfma_f32_16x16x32_bf16 v[14:17], v[62:65], v[218:221], v[14:17]
	v_mfma_f32_16x16x32_bf16 v[14:17], v[66:69], v[222:225], v[14:17]
	v_mfma_f32_16x16x32_bf16 v[10:13], v[74:77], v[218:221], v[10:13]
	v_mfma_f32_16x16x32_bf16 v[10:13], v[78:81], v[222:225], v[10:13]
	v_mfma_f32_16x16x32_bf16 v[54:57], v[146:149], v[190:193], v[54:57]
	v_mfma_f32_16x16x32_bf16 v[54:57], v[150:153], v[198:201], v[54:57]
	v_mfma_f32_16x16x32_bf16 v[50:53], v[154:157], v[190:193], v[50:53]
	v_mfma_f32_16x16x32_bf16 v[50:53], v[158:161], v[198:201], v[50:53]
	v_mfma_f32_16x16x32_bf16 v[38:41], v[146:149], v[202:205], v[38:41]
	v_mfma_f32_16x16x32_bf16 v[38:41], v[150:153], v[206:209], v[38:41]
	v_mfma_f32_16x16x32_bf16 v[34:37], v[154:157], v[202:205], v[34:37]
	v_mfma_f32_16x16x32_bf16 v[34:37], v[158:161], v[206:209], v[34:37]
	v_mfma_f32_16x16x32_bf16 v[22:25], v[146:149], v[210:213], v[22:25]
	v_mfma_f32_16x16x32_bf16 v[22:25], v[150:153], v[214:217], v[22:25]
	v_mfma_f32_16x16x32_bf16 v[18:21], v[154:157], v[210:213], v[18:21]
	v_mfma_f32_16x16x32_bf16 v[18:21], v[158:161], v[214:217], v[18:21]
	v_mfma_f32_16x16x32_bf16 v[6:9], v[146:149], v[218:221], v[6:9]
	v_mfma_f32_16x16x32_bf16 v[6:9], v[150:153], v[222:225], v[6:9]
	v_mfma_f32_16x16x32_bf16 v[2:5], v[154:157], v[218:221], v[2:5]
	v_mfma_f32_16x16x32_bf16 v[2:5], v[158:161], v[222:225], v[2:5]
	s_barrier
	s_add_i32 s54, s54, 2
	s_add_u32 s30, s30, 0x8000
	s_addc_u32 s31, s31, 0
	s_add_u32 s52, s52, 0x8000
	s_addc_u32 s53, s53, 0
	s_cmp_gt_u32 s54, 61
